# static s_setprio 3 for the RWKV chain block while its partner converts weights
# baseline (speedup 1.0000x reference)
; DEVI int TID() { int t = threadIdx.x; asm volatile("" : "+v"(t)); return t; }
; DEVI void rw_chain_task(const Params& p, int l, int seq, int head, int quarter, char* smem) {
;   const int tid = TID(), lane = tid & 63, wave = tid >> 6;
;   const int jl = lane & 15;
;   const int i = quarter * 16 + wave * 4 + (lane >> 4);
;   const int T = seq < 2 ? SEQ : 32;
;   const int nch = T >> 4;
;   const size_t gbase = seq < 2 ? (size_t)seq * SEQ : (size_t)NP + (seq - 2) * 32;
;   const u16* zC = (const u16*)(p.ws + W_ZC);
;   const u16* KK = (const u16*)(p.ws + W_KK);
;   const u16* BB = (const u16*)(p.ws + W_BB);
;   const float* WW = (const float*)(p.ws + W_WW);
;   u16* cat = (u16*)(p.ws + W_XN);
;   float S[4];
;   if (seq < 2) { S[0] = S[1] = S[2] = S[3] = 0.f; }
;   else {
;     float4 s0 = *(const float4*)(p.in[6] + ((((size_t)l * 8 + (seq - 2)) * 12 + head) * 64 + i) * 64 + jl * 4);
;     S[0] = s0.x; S[1] = s0.y; S[2] = s0.z; S[3] = s0.w;
;   }
;   typedef const __attribute__((address_space(1))) char* gptr_t;
;   typedef const __attribute__((address_space(1))) u32x4* gv4_t;
;   gptr_t lsrc0;
;   int lstride0, ldstA0, ldB;
;   {
;     const int step = tid >> 6;
;     int q = tid & 63;
;     if (q >= 56) q -= 8;
;     const size_t g = gbase + step;
;     if (q < 32) {
;       const int arr = q >> 3, qq = q & 7;
;       int off;
;       if (arr == 0) { lsrc0 = (gptr_t)(zC + g * LZC + head * 64 + qq * 8); lstride0 = LZC * 2; off = 24; }
;       else if (arr == 1) { lsrc0 = (gptr_t)(zC + g * LZC + 768 + head * 64 + qq * 8); lstride0 = LZC * 2; off = 16; }
;       else if (arr == 2) { lsrc0 = (gptr_t)(KK + g * 768 + head * 64 + qq * 8); lstride0 = 768 * 2; off = 0; }
;       else { lsrc0 = (gptr_t)(BB + g * 768 + head * 64 + qq * 8); lstride0 = 768 * 2; off = 8; }
;       ldstA0 = step * 896 + (2 * qq) * 48 + off;
;       ldB = 48;
;     } else if (q < 48) {
;       lsrc0 = (gptr_t)(WW + g * 768 + head * 64 + (q - 32) * 4); lstride0 = 768 * 4;
;       ldstA0 = step * 896 + (q - 32) * 48 + 32;
;       ldB = 8;
;     } else {
;       lsrc0 = (gptr_t)(zC + g * LZC + 1536 + head * 64 + (q - 48) * 8); lstride0 = LZC * 2;
;       ldstA0 = step * 896 + 768 + (q - 48) * 16;
;       ldB = 8;
;     }
;   }
;     ...
;   RW_LOAD(R0, 0);
;   RW_LOAD(R1, 1);
;   RW_LOAD(R2, 2);
;   RW_LOAD(R3, 3);
.LBB0_975:
	s_waitcnt vmcnt(0) lgkmcnt(0)
	s_barrier
	s_setprio 3
	v_readlane_b32 s38, v251, 1
	v_readlane_b32 s39, v251, 2
	v_readlane_b32 s41, v253, 37
	v_readlane_b32 s42, v253, 4
	v_readlane_b32 s43, v252, 61
	v_and_b32_e32 v3, 15, v1
	v_lshrrev_b32_e32 v5, 6, v1
	v_bfe_u32 v6, v1, 4, 2
	v_lshl_add_u32 v154, v5, 2, v6
	s_lshl_b32 s45, s41, 14
	s_lshl_b32 s46, s42, 7
	s_lshl_b32 s47, s41, 26
	v_add_u32_e32 v154, s43, v154
	v_and_b32_e32 v7, 31, v1
	v_lshrrev_b32_e32 v8, 3, v7
	v_and_b32_e32 v9, 7, v1
	v_lshrrev_b32_e32 v10, 5, v1
	v_lshrrev_b32_e32 v11, 1, v8
	v_and_b32_e32 v12, 1, v8
	v_cmp_ne_u32_e64 s[4:5], 0, v12
	v_cmp_ne_u32_e64 s[6:7], 0, v11
	v_mov_b32_e32 v14, 0x1cfd0000
	v_mov_b32_e32 v15, 0x1cfd0600
	v_mov_b32_e32 v16, 0x318b3000
	v_mov_b32_e32 v17, 0x34913000
	v_cndmask_b32_e64 v14, v14, v15, s[4:5]
	v_cndmask_b32_e64 v16, v16, v17, s[4:5]
	v_cndmask_b32_e64 v14, v14, v16, s[6:7]
	v_mov_b32_e32 v15, 0x1400
	v_mov_b32_e32 v17, 0x600
	v_cndmask_b32_e64 v13, v15, v17, s[6:7]
	v_xor_b32_e32 v18, 3, v8
	v_xor_b32_e32 v19, 2, v8
	v_cndmask_b32_e64 v18, v18, v19, s[6:7]
	v_lshl_add_u32 v14, v9, 4, v14
	v_add_u32_e32 v14, s46, v14
	v_add_u32_e32 v20, s45, v10
	v_mad_u32_u24 v14, v20, v13, v14
	v_mov_b32_e32 v15, 0
	v_lshl_add_u64 v[144:145], v[14:15], 0, s[38:39]
	v_lshlrev_b32_e32 v16, 3, v13
	v_mov_b32_e32 v17, 0
	v_lshl_add_u64 v[146:147], v[144:145], 0, v[16:17]
	v_lshlrev_b32_e32 v152, 4, v13
	v_mov_b32_e32 v153, 0
	v_mul_u32_u24_e32 v164, 0x580, v10
	v_mul_u32_u24_e32 v21, 0xa0, v9
	v_add_u32_e32 v164, v164, v21
	v_lshl_add_u32 v164, v18, 4, v164
	v_lshrrev_b32_e32 v22, 4, v1
	v_add_u32_e32 v20, s45, v22
	v_mov_b32_e32 v14, 0x37973000
	v_lshl_add_u32 v14, v3, 4, v14
	v_lshl_add_u32 v14, s42, 8, v14
	v_mov_b32_e32 v13, 0xc00
	v_mad_u32_u24 v14, v20, v13, v14
	v_lshl_add_u64 v[148:149], v[14:15], 0, s[38:39]
	v_mul_u32_u24_e32 v167, 0x580, v22
	v_mul_u32_u24_e32 v21, 0x50, v3
	v_add3_u32 v167, v167, v21, 64
	v_bfe_u32 v23, v1, 1, 3
	v_mov_b32_e32 v14, 0x1cfd0c00
	v_lshl_add_u32 v14, v23, 4, v14
	v_add_u32_e32 v14, s46, v14
	v_mov_b32_e32 v13, 0x1400
	v_mad_u32_u24 v14, v20, v13, v14
	v_lshl_add_u64 v[150:151], v[14:15], 0, s[38:39]
	v_mul_u32_u24_e32 v168, 0x580, v22
	v_lshl_add_u32 v168, v23, 4, v168
	v_add_u32_e32 v168, 0x500, v168
	v_mov_b32_e32 v62, 0xc000
	v_mov_b32_e32 v63, 0
	v_mov_b32_e32 v64, 0x14000
	v_mov_b32_e32 v65, 0
	v_mul_u32_u24_e32 v162, 0x50, v3
	v_lshlrev_b32_e32 v163, 1, v154
	v_add_u32_e32 v163, 0x500, v163
	v_lshlrev_b32_e32 v14, 12, v3
	v_lshl_add_u32 v14, v154, 1, v14
	v_add_u32_e32 v14, s47, v14
	v_add_u32_e32 v14, s46, v14
	v_add_u32_e32 v14, 0x2480a00, v14
	v_lshl_add_u64 v[160:161], v[14:15], 0, s[38:39]
	global_load_dwordx4 v[72:75], v[144:145], off
	global_load_dwordx4 v[76:79], v[146:147], off
	global_load_dwordx4 v[80:83], v[148:149], off
	global_load_dwordx4 v[84:87], v[150:151], off
	v_lshl_add_u64 v[144:145], v[144:145], 0, v[152:153]
	v_lshl_add_u64 v[146:147], v[146:147], 0, v[152:153]
	v_lshl_add_u64 v[148:149], v[148:149], 0, v[62:63]
	v_lshl_add_u64 v[150:151], v[150:151], 0, v[64:65]
	global_load_dwordx4 v[88:91], v[144:145], off
	global_load_dwordx4 v[92:95], v[146:147], off
	global_load_dwordx4 v[96:99], v[148:149], off
	global_load_dwordx4 v[100:103], v[150:151], off
	v_lshl_add_u64 v[144:145], v[144:145], 0, v[152:153]
	v_lshl_add_u64 v[146:147], v[146:147], 0, v[152:153]
	v_lshl_add_u64 v[148:149], v[148:149], 0, v[62:63]
	v_lshl_add_u64 v[150:151], v[150:151], 0, v[64:65]
	global_load_dwordx4 v[104:107], v[144:145], off
	global_load_dwordx4 v[108:111], v[146:147], off
	global_load_dwordx4 v[112:115], v[148:149], off
	global_load_dwordx4 v[116:119], v[150:151], off
	v_lshl_add_u64 v[144:145], v[144:145], 0, v[152:153]
	v_lshl_add_u64 v[146:147], v[146:147], 0, v[152:153]
	v_lshl_add_u64 v[148:149], v[148:149], 0, v[62:63]
	v_lshl_add_u64 v[150:151], v[150:151], 0, v[64:65]
	global_load_dwordx4 v[120:123], v[144:145], off
	global_load_dwordx4 v[124:127], v[146:147], off
	global_load_dwordx4 v[128:131], v[148:149], off
	global_load_dwordx4 v[132:135], v[150:151], off
	v_lshl_add_u64 v[144:145], v[144:145], 0, v[152:153]
	v_lshl_add_u64 v[146:147], v[146:147], 0, v[152:153]
	v_lshl_add_u64 v[148:149], v[148:149], 0, v[62:63]
	v_lshl_add_u64 v[150:151], v[150:151], 0, v[64:65]
	v_and_b32_e32 v14, 2, v3
	v_and_b32_e32 v15, 1, v3
	v_cmp_ne_u32_e64 s[4:5], 0, v14
	v_cmp_ne_u32_e64 s[6:7], 0, v15
	v_mov_b32_e32 v68, 0
	v_mov_b32_e32 v69, 0
	v_mov_b32_e32 v70, 0
	v_mov_b32_e32 v71, 0
	v_mov_b32_e32 v60, 0
	v_mov_b32_e32 v24, 0
	v_mov_b32_e32 v48, 0
	s_mov_b32 s46, 0x10000
	s_mov_b32 s47, 0
	v_mov_b32_e32 v155, v164
	v_mov_b32_e32 v165, v167
	v_mov_b32_e32 v166, v168
	s_waitcnt vmcnt(12)
; DEVI void rw_chain_task(const Params& p, int l, int seq, int head, int quarter, char* smem) {
;     ...
;   RW_LOAD(R0, 0);
;   RW_LOAD(R1, 1);
;   RW_LOAD(R2, 2);
;   RW_LOAD(R3, 3);
;   RW_STORE(R0, B0);
;   RW_LOAD(R0, 4);
;   if (seq < 2) {
;     for (int c = 0; c < nch; c += 4) {
;       lds_barrier();
;       RW_STORE(R1, B1);
	v_lshlrev_b32_e32 v136, 16, v72
	v_and_b32_e32 v137, 0xffff0000, v72
	v_lshlrev_b32_e32 v138, 16, v73
	v_and_b32_e32 v139, 0xffff0000, v73
	v_lshlrev_b32_e32 v140, 16, v74
	v_and_b32_e32 v141, 0xffff0000, v74
	v_lshlrev_b32_e32 v142, 16, v75
	v_and_b32_e32 v143, 0xffff0000, v75
	ds_write_b128 v155, v[136:139] offset:0
	ds_write_b128 v155, v[140:143] offset:80
	v_lshlrev_b32_e32 v136, 16, v76
	v_and_b32_e32 v137, 0xffff0000, v76
	v_lshlrev_b32_e32 v138, 16, v77
	v_and_b32_e32 v139, 0xffff0000, v77
	v_lshlrev_b32_e32 v140, 16, v78
	v_and_b32_e32 v141, 0xffff0000, v78
	v_lshlrev_b32_e32 v142, 16, v79
	v_and_b32_e32 v143, 0xffff0000, v79
	ds_write_b128 v155, v[136:139] offset:11264
	ds_write_b128 v155, v[140:143] offset:11344
	ds_write_b128 v165, v[80:83]
	ds_write_b128 v166, v[84:87]
	global_load_dwordx4 v[72:75], v[144:145], off
	global_load_dwordx4 v[76:79], v[146:147], off
	global_load_dwordx4 v[80:83], v[148:149], off
	global_load_dwordx4 v[84:87], v[150:151], off
	v_lshl_add_u64 v[144:145], v[144:145], 0, v[152:153]
	v_lshl_add_u64 v[146:147], v[146:147], 0, v[152:153]
	v_lshl_add_u64 v[148:149], v[148:149], 0, v[62:63]
	v_lshl_add_u64 v[150:151], v[150:151], 0, v[64:65]
	v_add_u32_e32 v155, 0x5800, v164
	v_add_u32_e32 v165, 0x5800, v167
	v_add_u32_e32 v166, 0x5800, v168
	s_waitcnt vmcnt(12)
	v_lshlrev_b32_e32 v136, 16, v88
	v_and_b32_e32 v137, 0xffff0000, v88
	v_lshlrev_b32_e32 v138, 16, v89
	v_and_b32_e32 v139, 0xffff0000, v89
	v_lshlrev_b32_e32 v140, 16, v90
	v_and_b32_e32 v141, 0xffff0000, v90
	v_lshlrev_b32_e32 v142, 16, v91
	v_and_b32_e32 v143, 0xffff0000, v91
	ds_write_b128 v155, v[136:139] offset:0
	ds_write_b128 v155, v[140:143] offset:80
	v_lshlrev_b32_e32 v136, 16, v92
	v_and_b32_e32 v137, 0xffff0000, v92
	v_lshlrev_b32_e32 v138, 16, v93
	v_and_b32_e32 v139, 0xffff0000, v93
	v_lshlrev_b32_e32 v140, 16, v94
	v_and_b32_e32 v141, 0xffff0000, v94
	v_lshlrev_b32_e32 v142, 16, v95
	v_and_b32_e32 v143, 0xffff0000, v95
	ds_write_b128 v155, v[136:139] offset:11264
	ds_write_b128 v155, v[140:143] offset:11344
	ds_write_b128 v165, v[96:99]
	ds_write_b128 v166, v[100:103]
	global_load_dwordx4 v[88:91], v[144:145], off
	global_load_dwordx4 v[92:95], v[146:147], off
	global_load_dwordx4 v[96:99], v[148:149], off
	global_load_dwordx4 v[100:103], v[150:151], off
	v_lshl_add_u64 v[144:145], v[144:145], 0, v[152:153]
	v_lshl_add_u64 v[146:147], v[146:147], 0, v[152:153]
	v_lshl_add_u64 v[148:149], v[148:149], 0, v[62:63]
	v_lshl_add_u64 v[150:151], v[150:151], 0, v[64:65]
	s_mov_b32 s42, 0xb000
	s_mov_b32 s43, 0
	s_mov_b32 s45, 0x5800
	s_mov_b32 s41, 0
	s_waitcnt lgkmcnt(0)
	s_barrier
	ds_read_b128 v[16:19], v162 offset:48
	ds_read_b128 v[4:7], v162 offset:0
	ds_read_b128 v[8:11], v162 offset:16
	ds_read_b128 v[12:15], v162 offset:32
	ds_read_b128 v[20:23], v162 offset:64
	ds_read_u16_d16_hi v24, v163 offset:0

; DEVI void rw_chain_task(const Params& p, int l, int seq, int head, int quarter, char* smem) {
;     ...
;       lds_barrier();
;       RW_STORE(R1, B1);
;       RW_LOAD(R1, c + 5);
;       RW_COMPUTE(B0, c);
;       lds_barrier();
;       RW_STORE(R2, B0);
;       RW_LOAD(R2, c + 6);
.Lrwc_nostore:
	v_add_f32_dpp v174, v174, v174 row_ror:1 row_mask:0xf bank_mask:0xf bound_ctrl:1
	v_pk_fma_f32 v[68:69], v[174:175], v[32:33], v[56:57] op_sel_hi:[0,1,1] neg_lo:[1,0,0] neg_hi:[1,0,0]
	v_pk_fma_f32 v[70:71], v[174:175], v[34:35], v[58:59] op_sel_hi:[0,1,1] neg_lo:[1,0,0] neg_hi:[1,0,0]
	s_waitcnt lgkmcnt(0)
	s_barrier
	s_mov_b32 vcc_lo, s42
	s_mov_b32 s42, s43
	s_mov_b32 s43, s45
	s_mov_b32 s45, vcc_lo
	v_add_u32_e32 v156, s42, v162
	v_add_u32_e32 v157, s42, v163
	v_add_u32_e32 v155, s45, v164
	v_add_u32_e32 v165, s45, v167
	v_add_u32_e32 v166, s45, v168
	s_waitcnt lgkmcnt(0)
	ds_read_b128 v[28:31], v156 offset:1408
	ds_read_b128 v[36:39], v156 offset:1440
	ds_read_u16_d16_hi v48, v157 offset:1408
	ds_read_b128 v[44:47], v156 offset:1472
	ds_read_b128 v[32:35], v156 offset:1424
	v_pk_mul_f32 v[172:173], v[68:69], v[4:5]
	v_pk_mul_f32 v[178:179], v[68:69], v[40:41]
	v_pk_fma_f32 v[172:173], v[70:71], v[6:7], v[172:173]
	v_pk_fma_f32 v[178:179], v[70:71], v[42:43], v[178:179]
	v_add_f32_e32 v172, v172, v173
	v_add_f32_e32 v195, v178, v179
	v_pk_mul_f32 v[52:53], v[24:25], v[12:13] op_sel_hi:[0,1]
	ds_read_b128 v[40:43], v156 offset:1456
	v_add_f32_dpp v172, v172, v172 row_ror:8 row_mask:0xf bank_mask:0xf bound_ctrl:1
	v_pk_mul_f32 v[54:55], v[24:25], v[14:15] op_sel_hi:[0,1]
	v_pk_fma_f32 v[56:57], v[68:69], v[20:21], v[52:53]
	v_add_f32_dpp v172, v172, v172 row_ror:4 row_mask:0xf bank_mask:0xf bound_ctrl:1
	v_pk_fma_f32 v[58:59], v[70:71], v[22:23], v[54:55]
	s_nop 0
	v_add_f32_dpp v172, v172, v172 row_ror:2 row_mask:0xf bank_mask:0xf bound_ctrl:1
	s_nop 1
	v_add_f32_dpp v172, v172, v172 row_ror:1 row_mask:0xf bank_mask:0xf bound_ctrl:1
	v_pk_fma_f32 v[68:69], v[172:173], v[8:9], v[56:57] op_sel_hi:[0,1,1] neg_lo:[1,0,0] neg_hi:[1,0,0]
	v_pk_fma_f32 v[70:71], v[172:173], v[10:11], v[58:59] op_sel_hi:[0,1,1] neg_lo:[1,0,0] neg_hi:[1,0,0]
	s_waitcnt lgkmcnt(0)
	ds_read_b128 v[4:7], v156 offset:2816
	ds_read_b128 v[12:15], v156 offset:2848
	ds_read_u16_d16_hi v24, v157 offset:2816
	ds_read_b128 v[20:23], v156 offset:2880
	ds_read_b128 v[8:11], v156 offset:2832
	v_pk_mul_f32 v[174:175], v[68:69], v[28:29]
	v_pk_mul_f32 v[176:177], v[68:69], v[16:17]
	v_pk_fma_f32 v[174:175], v[70:71], v[30:31], v[174:175]
	v_pk_fma_f32 v[176:177], v[70:71], v[18:19], v[176:177]
	v_add_f32_e32 v174, v174, v175
	v_add_f32_e32 v196, v176, v177
	v_pk_mul_f32 v[52:53], v[48:49], v[36:37] op_sel_hi:[0,1]
	ds_read_b128 v[16:19], v156 offset:2864
	v_add_f32_dpp v174, v174, v174 row_ror:8 row_mask:0xf bank_mask:0xf bound_ctrl:1
	v_pk_mul_f32 v[54:55], v[48:49], v[38:39] op_sel_hi:[0,1]
	v_pk_fma_f32 v[56:57], v[68:69], v[44:45], v[52:53]
	v_add_f32_dpp v174, v174, v174 row_ror:4 row_mask:0xf bank_mask:0xf bound_ctrl:1
	v_pk_fma_f32 v[58:59], v[70:71], v[46:47], v[54:55]
	s_waitcnt vmcnt(12)
	v_add_f32_dpp v174, v174, v174 row_ror:2 row_mask:0xf bank_mask:0xf bound_ctrl:1
	v_lshlrev_b32_e32 v136, 16, v120
	v_and_b32_e32 v137, 0xffff0000, v120
	v_add_f32_dpp v174, v174, v174 row_ror:1 row_mask:0xf bank_mask:0xf bound_ctrl:1
	v_add_f32_dpp v230, v180, v180 row_mirror row_mask:0xf bank_mask:0xf bound_ctrl:1
	v_add_f32_dpp v230, v188, v188 row_mirror row_mask:0xf bank_mask:0xc bound_ctrl:1
	v_pk_fma_f32 v[68:69], v[174:175], v[32:33], v[56:57] op_sel_hi:[0,1,1] neg_lo:[1,0,0] neg_hi:[1,0,0]
	v_pk_fma_f32 v[70:71], v[174:175], v[34:35], v[58:59] op_sel_hi:[0,1,1] neg_lo:[1,0,0] neg_hi:[1,0,0]
	s_waitcnt lgkmcnt(0)
	ds_read_b128 v[28:31], v156 offset:4224
	ds_read_b128 v[36:39], v156 offset:4256
	ds_read_u16_d16_hi v48, v157 offset:4224
	ds_read_b128 v[44:47], v156 offset:4288
	ds_read_b128 v[32:35], v156 offset:4240
	v_pk_mul_f32 v[172:173], v[68:69], v[4:5]
	v_pk_mul_f32 v[178:179], v[68:69], v[40:41]
	v_pk_fma_f32 v[172:173], v[70:71], v[6:7], v[172:173]
	v_pk_fma_f32 v[178:179], v[70:71], v[42:43], v[178:179]
	v_add_f32_e32 v172, v172, v173
	v_add_f32_e32 v197, v178, v179
	v_pk_mul_f32 v[52:53], v[24:25], v[12:13] op_sel_hi:[0,1]
	ds_read_b128 v[40:43], v156 offset:4272
	v_add_f32_dpp v172, v172, v172 row_ror:8 row_mask:0xf bank_mask:0xf bound_ctrl:1
	v_pk_mul_f32 v[54:55], v[24:25], v[14:15] op_sel_hi:[0,1]
	v_pk_fma_f32 v[56:57], v[68:69], v[20:21], v[52:53]
	v_add_f32_dpp v172, v172, v172 row_ror:4 row_mask:0xf bank_mask:0xf bound_ctrl:1
	v_pk_fma_f32 v[58:59], v[70:71], v[22:23], v[54:55]
	v_lshlrev_b32_e32 v138, 16, v121
	v_add_f32_dpp v172, v172, v172 row_ror:2 row_mask:0xf bank_mask:0xf bound_ctrl:1
	v_and_b32_e32 v139, 0xffff0000, v121
	v_lshlrev_b32_e32 v140, 16, v122
	v_add_f32_dpp v172, v172, v172 row_ror:1 row_mask:0xf bank_mask:0xf bound_ctrl:1
	v_add_f32_dpp v231, v181, v181 row_mirror row_mask:0xf bank_mask:0xf bound_ctrl:1
	v_add_f32_dpp v231, v189, v189 row_mirror row_mask:0xf bank_mask:0xc bound_ctrl:1
	v_pk_fma_f32 v[68:69], v[172:173], v[8:9], v[56:57] op_sel_hi:[0,1,1] neg_lo:[1,0,0] neg_hi:[1,0,0]
	v_pk_fma_f32 v[70:71], v[172:173], v[10:11], v[58:59] op_sel_hi:[0,1,1] neg_lo:[1,0,0] neg_hi:[1,0,0]
	s_waitcnt lgkmcnt(0)
	ds_read_b128 v[4:7], v156 offset:5632
	ds_read_b128 v[12:15], v156 offset:5664
	ds_read_u16_d16_hi v24, v157 offset:5632
	ds_read_b128 v[20:23], v156 offset:5696
	ds_read_b128 v[8:11], v156 offset:5648
	v_pk_mul_f32 v[174:175], v[68:69], v[28:29]
	v_pk_mul_f32 v[176:177], v[68:69], v[16:17]
	v_pk_fma_f32 v[174:175], v[70:71], v[30:31], v[174:175]
	v_pk_fma_f32 v[176:177], v[70:71], v[18:19], v[176:177]
	v_add_f32_e32 v174, v174, v175
	v_add_f32_e32 v198, v176, v177
	v_pk_mul_f32 v[52:53], v[48:49], v[36:37] op_sel_hi:[0,1]
	ds_read_b128 v[16:19], v156 offset:5680
	v_add_f32_dpp v174, v174, v174 row_ror:8 row_mask:0xf bank_mask:0xf bound_ctrl:1
	v_pk_mul_f32 v[54:55], v[48:49], v[38:39] op_sel_hi:[0,1]
	v_pk_fma_f32 v[56:57], v[68:69], v[44:45], v[52:53]
	v_add_f32_dpp v174, v174, v174 row_ror:4 row_mask:0xf bank_mask:0xf bound_ctrl:1
	v_pk_fma_f32 v[58:59], v[70:71], v[46:47], v[54:55]
	v_and_b32_e32 v141, 0xffff0000, v122
	v_add_f32_dpp v174, v174, v174 row_ror:2 row_mask:0xf bank_mask:0xf bound_ctrl:1
	v_lshlrev_b32_e32 v142, 16, v123
	v_and_b32_e32 v143, 0xffff0000, v123
	v_add_f32_dpp v174, v174, v174 row_ror:1 row_mask:0xf bank_mask:0xf bound_ctrl:1
	v_add_f32_dpp v232, v182, v182 row_mirror row_mask:0xf bank_mask:0xf bound_ctrl:1
	v_add_f32_dpp v232, v190, v190 row_mirror row_mask:0xf bank_mask:0xc bound_ctrl:1
	v_pk_fma_f32 v[68:69], v[174:175], v[32:33], v[56:57] op_sel_hi:[0,1,1] neg_lo:[1,0,0] neg_hi:[1,0,0]
	v_pk_fma_f32 v[70:71], v[174:175], v[34:35], v[58:59] op_sel_hi:[0,1,1] neg_lo:[1,0,0] neg_hi:[1,0,0]
	s_waitcnt lgkmcnt(0)
	ds_read_b128 v[28:31], v156 offset:7040
	ds_read_b128 v[36:39], v156 offset:7072
	ds_read_u16_d16_hi v48, v157 offset:7040
	ds_read_b128 v[44:47], v156 offset:7104
	ds_read_b128 v[32:35], v156 offset:7056
	v_pk_mul_f32 v[172:173], v[68:69], v[4:5]
	v_pk_mul_f32 v[178:179], v[68:69], v[40:41]
	v_pk_fma_f32 v[172:173], v[70:71], v[6:7], v[172:173]
	v_pk_fma_f32 v[178:179], v[70:71], v[42:43], v[178:179]
	v_add_f32_e32 v172, v172, v173
	v_add_f32_e32 v199, v178, v179
	v_pk_mul_f32 v[52:53], v[24:25], v[12:13] op_sel_hi:[0,1]
	ds_read_b128 v[40:43], v156 offset:7088
	v_add_f32_dpp v172, v172, v172 row_ror:8 row_mask:0xf bank_mask:0xf bound_ctrl:1
	v_pk_mul_f32 v[54:55], v[24:25], v[14:15] op_sel_hi:[0,1]
	v_pk_fma_f32 v[56:57], v[68:69], v[20:21], v[52:53]
	v_add_f32_dpp v172, v172, v172 row_ror:4 row_mask:0xf bank_mask:0xf bound_ctrl:1
	v_pk_fma_f32 v[58:59], v[70:71], v[22:23], v[54:55]
	ds_write_b128 v155, v[136:139] offset:0
	v_add_f32_dpp v172, v172, v172 row_ror:2 row_mask:0xf bank_mask:0xf bound_ctrl:1
	ds_write_b128 v155, v[140:143] offset:80
	v_lshlrev_b32_e32 v136, 16, v124
	v_add_f32_dpp v172, v172, v172 row_ror:1 row_mask:0xf bank_mask:0xf bound_ctrl:1
	v_add_f32_dpp v233, v183, v183 row_mirror row_mask:0xf bank_mask:0xf bound_ctrl:1
	v_add_f32_dpp v233, v191, v191 row_mirror row_mask:0xf bank_mask:0xc bound_ctrl:1
	v_pk_fma_f32 v[68:69], v[172:173], v[8:9], v[56:57] op_sel_hi:[0,1,1] neg_lo:[1,0,0] neg_hi:[1,0,0]
	v_pk_fma_f32 v[70:71], v[172:173], v[10:11], v[58:59] op_sel_hi:[0,1,1] neg_lo:[1,0,0] neg_hi:[1,0,0]
	v_add_f32_dpp v234, v184, v184 row_mirror row_mask:0xf bank_mask:0xf bound_ctrl:1
	s_waitcnt lgkmcnt(2)
	ds_read_b128 v[4:7], v156 offset:8448
	ds_read_b128 v[12:15], v156 offset:8480
	ds_read_u16_d16_hi v24, v157 offset:8448
	ds_read_b128 v[20:23], v156 offset:8512
	ds_read_b128 v[8:11], v156 offset:8464
	v_pk_mul_f32 v[174:175], v[68:69], v[28:29]
	v_pk_mul_f32 v[176:177], v[68:69], v[16:17]
	v_pk_fma_f32 v[174:175], v[70:71], v[30:31], v[174:175]
	v_pk_fma_f32 v[176:177], v[70:71], v[18:19], v[176:177]
	v_add_f32_e32 v174, v174, v175
	v_add_f32_e32 v200, v176, v177
	v_pk_mul_f32 v[52:53], v[48:49], v[36:37] op_sel_hi:[0,1]
	ds_read_b128 v[16:19], v156 offset:8496
	v_add_f32_dpp v174, v174, v174 row_ror:8 row_mask:0xf bank_mask:0xf bound_ctrl:1
	v_pk_mul_f32 v[54:55], v[48:49], v[38:39] op_sel_hi:[0,1]
	v_pk_fma_f32 v[56:57], v[68:69], v[44:45], v[52:53]
	v_add_f32_dpp v174, v174, v174 row_ror:4 row_mask:0xf bank_mask:0xf bound_ctrl:1
	v_pk_fma_f32 v[58:59], v[70:71], v[46:47], v[54:55]
	v_and_b32_e32 v137, 0xffff0000, v124
	v_add_f32_dpp v174, v174, v174 row_ror:2 row_mask:0xf bank_mask:0xf bound_ctrl:1
	v_lshlrev_b32_e32 v138, 16, v125
	v_and_b32_e32 v139, 0xffff0000, v125
	v_add_f32_dpp v174, v174, v174 row_ror:1 row_mask:0xf bank_mask:0xf bound_ctrl:1
	v_add_f32_dpp v234, v192, v192 row_mirror row_mask:0xf bank_mask:0xc bound_ctrl:1
	v_add_f32_dpp v235, v185, v185 row_mirror row_mask:0xf bank_mask:0xf bound_ctrl:1
	v_pk_fma_f32 v[68:69], v[174:175], v[32:33], v[56:57] op_sel_hi:[0,1,1] neg_lo:[1,0,0] neg_hi:[1,0,0]
	v_pk_fma_f32 v[70:71], v[174:175], v[34:35], v[58:59] op_sel_hi:[0,1,1] neg_lo:[1,0,0] neg_hi:[1,0,0]
	s_waitcnt lgkmcnt(0)
	ds_read_b128 v[28:31], v156 offset:9856
	ds_read_b128 v[36:39], v156 offset:9888
	ds_read_u16_d16_hi v48, v157 offset:9856
	ds_read_b128 v[44:47], v156 offset:9920
	ds_read_b128 v[32:35], v156 offset:9872
	v_pk_mul_f32 v[172:173], v[68:69], v[4:5]
	v_pk_mul_f32 v[178:179], v[68:69], v[40:41]
	v_pk_fma_f32 v[172:173], v[70:71], v[6:7], v[172:173]
	v_pk_fma_f32 v[178:179], v[70:71], v[42:43], v[178:179]
	v_add_f32_e32 v172, v172, v173
	v_add_f32_e32 v201, v178, v179
	v_pk_mul_f32 v[52:53], v[24:25], v[12:13] op_sel_hi:[0,1]
	ds_read_b128 v[40:43], v156 offset:9904
	v_add_f32_dpp v172, v172, v172 row_ror:8 row_mask:0xf bank_mask:0xf bound_ctrl:1
	v_pk_mul_f32 v[54:55], v[24:25], v[14:15] op_sel_hi:[0,1]
	v_pk_fma_f32 v[56:57], v[68:69], v[20:21], v[52:53]
	v_add_f32_dpp v172, v172, v172 row_ror:4 row_mask:0xf bank_mask:0xf bound_ctrl:1
	v_pk_fma_f32 v[58:59], v[70:71], v[22:23], v[54:55]
	v_lshlrev_b32_e32 v140, 16, v126
	v_add_f32_dpp v172, v172, v172 row_ror:2 row_mask:0xf bank_mask:0xf bound_ctrl:1
	v_and_b32_e32 v141, 0xffff0000, v126
	v_lshlrev_b32_e32 v142, 16, v127
	v_add_f32_dpp v172, v172, v172 row_ror:1 row_mask:0xf bank_mask:0xf bound_ctrl:1
	v_add_f32_dpp v235, v193, v193 row_mirror row_mask:0xf bank_mask:0xc bound_ctrl:1
	v_add_f32_dpp v236, v186, v186 row_mirror row_mask:0xf bank_mask:0xf bound_ctrl:1
	v_pk_fma_f32 v[68:69], v[172:173], v[8:9], v[56:57] op_sel_hi:[0,1,1] neg_lo:[1,0,0] neg_hi:[1,0,0]
	v_pk_fma_f32 v[70:71], v[172:173], v[10:11], v[58:59] op_sel_hi:[0,1,1] neg_lo:[1,0,0] neg_hi:[1,0,0]
	s_waitcnt lgkmcnt(0)
; DEVI void rw_chain_task(const Params& p, int l, int seq, int head, int quarter, char* smem) {
;     ...
;     for (int c = 0; c < nch; c += 4) {
;       lds_barrier();
;       RW_STORE(R1, B1);
;       RW_LOAD(R1, c + 5);
;       RW_COMPUTE(B0, c);
;       lds_barrier();
;       RW_STORE(R2, B0);
;       RW_LOAD(R2, c + 6);
;       RW_COMPUTE(B1, c + 1);
;       lds_barrier();
;       RW_STORE(R3, B1);
;       RW_LOAD(R3, c + 7);
;       RW_COMPUTE(B0, c + 2);
;       lds_barrier();
;       RW_STORE(R0, B0);
;       RW_LOAD(R0, c + 8);
;       RW_COMPUTE(B1, c + 3);
;     }
	ds_read_b128 v[4:7], v156 offset:11264
	ds_read_b128 v[12:15], v156 offset:11296
	ds_read_u16_d16_hi v24, v157 offset:11264
	ds_read_b128 v[20:23], v156 offset:11328
	ds_read_b128 v[8:11], v156 offset:11280
	v_pk_mul_f32 v[174:175], v[68:69], v[28:29]
	v_pk_mul_f32 v[176:177], v[68:69], v[16:17]
	v_pk_fma_f32 v[174:175], v[70:71], v[30:31], v[174:175]
	v_pk_fma_f32 v[176:177], v[70:71], v[18:19], v[176:177]
	v_add_f32_e32 v174, v174, v175
	v_add_f32_e32 v210, v176, v177
	v_pk_mul_f32 v[52:53], v[48:49], v[36:37] op_sel_hi:[0,1]
	ds_read_b128 v[16:19], v156 offset:11312
	v_add_f32_dpp v174, v174, v174 row_ror:8 row_mask:0xf bank_mask:0xf bound_ctrl:1
	v_pk_mul_f32 v[54:55], v[48:49], v[38:39] op_sel_hi:[0,1]
	v_pk_fma_f32 v[56:57], v[68:69], v[44:45], v[52:53]
	v_add_f32_dpp v174, v174, v174 row_ror:4 row_mask:0xf bank_mask:0xf bound_ctrl:1
	v_pk_fma_f32 v[58:59], v[70:71], v[46:47], v[54:55]
	v_and_b32_e32 v143, 0xffff0000, v127
	v_add_f32_dpp v174, v174, v174 row_ror:2 row_mask:0xf bank_mask:0xf bound_ctrl:1
	ds_write_b128 v155, v[136:139] offset:11264
	ds_write_b128 v155, v[140:143] offset:11344
	v_add_f32_dpp v174, v174, v174 row_ror:1 row_mask:0xf bank_mask:0xf bound_ctrl:1
	v_add_f32_dpp v236, v194, v194 row_mirror row_mask:0xf bank_mask:0xc bound_ctrl:1
	v_add_f32_dpp v237, v187, v187 row_mirror row_mask:0xf bank_mask:0xf bound_ctrl:1
	v_pk_fma_f32 v[68:69], v[174:175], v[32:33], v[56:57] op_sel_hi:[0,1,1] neg_lo:[1,0,0] neg_hi:[1,0,0]
	v_pk_fma_f32 v[70:71], v[174:175], v[34:35], v[58:59] op_sel_hi:[0,1,1] neg_lo:[1,0,0] neg_hi:[1,0,0]
	s_waitcnt lgkmcnt(2)
	ds_read_b128 v[28:31], v156 offset:12672
	ds_read_b128 v[36:39], v156 offset:12704
	ds_read_u16_d16_hi v48, v157 offset:12672
	ds_read_b128 v[44:47], v156 offset:12736
	ds_read_b128 v[32:35], v156 offset:12688
	v_pk_mul_f32 v[172:173], v[68:69], v[4:5]
	v_pk_mul_f32 v[178:179], v[68:69], v[40:41]
	v_pk_fma_f32 v[172:173], v[70:71], v[6:7], v[172:173]
	v_pk_fma_f32 v[178:179], v[70:71], v[42:43], v[178:179]
	v_add_f32_e32 v172, v172, v173
	v_add_f32_e32 v211, v178, v179
	v_pk_mul_f32 v[52:53], v[24:25], v[12:13] op_sel_hi:[0,1]
	ds_read_b128 v[40:43], v156 offset:12720
	v_add_f32_dpp v172, v172, v172 row_ror:8 row_mask:0xf bank_mask:0xf bound_ctrl:1
	v_pk_mul_f32 v[54:55], v[24:25], v[14:15] op_sel_hi:[0,1]
	v_pk_fma_f32 v[56:57], v[68:69], v[20:21], v[52:53]
	v_add_f32_dpp v172, v172, v172 row_ror:4 row_mask:0xf bank_mask:0xf bound_ctrl:1
	v_pk_fma_f32 v[58:59], v[70:71], v[22:23], v[54:55]
	ds_write_b128 v165, v[128:131]
	v_add_f32_dpp v172, v172, v172 row_ror:2 row_mask:0xf bank_mask:0xf bound_ctrl:1
	ds_write_b128 v166, v[132:135]
	global_load_dwordx4 v[120:123], v[144:145], off
	v_add_f32_dpp v172, v172, v172 row_ror:1 row_mask:0xf bank_mask:0xf bound_ctrl:1
	v_add_f32_dpp v237, v195, v195 row_mirror row_mask:0xf bank_mask:0xc bound_ctrl:1
	v_add_f32_dpp v238, v230, v230 row_half_mirror row_mask:0xf bank_mask:0xf bound_ctrl:1
	v_pk_fma_f32 v[68:69], v[172:173], v[8:9], v[56:57] op_sel_hi:[0,1,1] neg_lo:[1,0,0] neg_hi:[1,0,0]
	v_pk_fma_f32 v[70:71], v[172:173], v[10:11], v[58:59] op_sel_hi:[0,1,1] neg_lo:[1,0,0] neg_hi:[1,0,0]
	v_add_f32_dpp v238, v234, v234 row_half_mirror row_mask:0xf bank_mask:0xa bound_ctrl:1
	s_waitcnt lgkmcnt(2)
	ds_read_b128 v[4:7], v156 offset:14080
	ds_read_b128 v[12:15], v156 offset:14112
	ds_read_u16_d16_hi v24, v157 offset:14080
	ds_read_b128 v[20:23], v156 offset:14144
	ds_read_b128 v[8:11], v156 offset:14096
	v_pk_mul_f32 v[174:175], v[68:69], v[28:29]
	v_pk_mul_f32 v[176:177], v[68:69], v[16:17]
	v_pk_fma_f32 v[174:175], v[70:71], v[30:31], v[174:175]
	v_pk_fma_f32 v[176:177], v[70:71], v[18:19], v[176:177]
	v_add_f32_e32 v174, v174, v175
	v_add_f32_e32 v212, v176, v177
	v_pk_mul_f32 v[52:53], v[48:49], v[36:37] op_sel_hi:[0,1]
	ds_read_b128 v[16:19], v156 offset:14128
	v_add_f32_dpp v174, v174, v174 row_ror:8 row_mask:0xf bank_mask:0xf bound_ctrl:1
	v_pk_mul_f32 v[54:55], v[48:49], v[38:39] op_sel_hi:[0,1]
	v_pk_fma_f32 v[56:57], v[68:69], v[44:45], v[52:53]
	v_add_f32_dpp v174, v174, v174 row_ror:4 row_mask:0xf bank_mask:0xf bound_ctrl:1
	v_pk_fma_f32 v[58:59], v[70:71], v[46:47], v[54:55]
	global_load_dwordx4 v[124:127], v[146:147], off
	v_add_f32_dpp v174, v174, v174 row_ror:2 row_mask:0xf bank_mask:0xf bound_ctrl:1
	global_load_dwordx4 v[128:131], v[148:149], off
	global_load_dwordx4 v[132:135], v[150:151], off
	v_add_f32_dpp v174, v174, v174 row_ror:1 row_mask:0xf bank_mask:0xf bound_ctrl:1
	v_add_f32_dpp v239, v231, v231 row_half_mirror row_mask:0xf bank_mask:0xf bound_ctrl:1
	v_add_f32_dpp v239, v235, v235 row_half_mirror row_mask:0xf bank_mask:0xa bound_ctrl:1
	v_pk_fma_f32 v[68:69], v[174:175], v[32:33], v[56:57] op_sel_hi:[0,1,1] neg_lo:[1,0,0] neg_hi:[1,0,0]
	v_pk_fma_f32 v[70:71], v[174:175], v[34:35], v[58:59] op_sel_hi:[0,1,1] neg_lo:[1,0,0] neg_hi:[1,0,0]
	s_waitcnt lgkmcnt(0)
	ds_read_b128 v[28:31], v156 offset:15488
	ds_read_b128 v[36:39], v156 offset:15520
	ds_read_u16_d16_hi v48, v157 offset:15488
	ds_read_b128 v[44:47], v156 offset:15552
	ds_read_b128 v[32:35], v156 offset:15504
	v_pk_mul_f32 v[172:173], v[68:69], v[4:5]
	v_pk_mul_f32 v[178:179], v[68:69], v[40:41]
	v_pk_fma_f32 v[172:173], v[70:71], v[6:7], v[172:173]
	v_pk_fma_f32 v[178:179], v[70:71], v[42:43], v[178:179]
	v_add_f32_e32 v172, v172, v173
	v_add_f32_e32 v213, v178, v179
	v_pk_mul_f32 v[52:53], v[24:25], v[12:13] op_sel_hi:[0,1]
	ds_read_b128 v[40:43], v156 offset:15536
	v_add_f32_dpp v172, v172, v172 row_ror:8 row_mask:0xf bank_mask:0xf bound_ctrl:1
	v_pk_mul_f32 v[54:55], v[24:25], v[14:15] op_sel_hi:[0,1]
	v_pk_fma_f32 v[56:57], v[68:69], v[20:21], v[52:53]
	v_add_f32_dpp v172, v172, v172 row_ror:4 row_mask:0xf bank_mask:0xf bound_ctrl:1
	v_pk_fma_f32 v[58:59], v[70:71], v[22:23], v[54:55]
	v_lshl_add_u64 v[144:145], v[144:145], 0, v[152:153]
	v_add_f32_dpp v172, v172, v172 row_ror:2 row_mask:0xf bank_mask:0xf bound_ctrl:1
	v_lshl_add_u64 v[146:147], v[146:147], 0, v[152:153]
	v_lshl_add_u64 v[148:149], v[148:149], 0, v[62:63]
	v_add_f32_dpp v172, v172, v172 row_ror:1 row_mask:0xf bank_mask:0xf bound_ctrl:1
	v_add_f32_dpp v240, v232, v232 row_half_mirror row_mask:0xf bank_mask:0xf bound_ctrl:1
	v_add_f32_dpp v240, v236, v236 row_half_mirror row_mask:0xf bank_mask:0xa bound_ctrl:1
	v_pk_fma_f32 v[68:69], v[172:173], v[8:9], v[56:57] op_sel_hi:[0,1,1] neg_lo:[1,0,0] neg_hi:[1,0,0]
	v_pk_fma_f32 v[70:71], v[172:173], v[10:11], v[58:59] op_sel_hi:[0,1,1] neg_lo:[1,0,0] neg_hi:[1,0,0]
	s_waitcnt lgkmcnt(0)
	ds_read_b128 v[4:7], v156 offset:16896
	ds_read_b128 v[12:15], v156 offset:16928
	ds_read_u16_d16_hi v24, v157 offset:16896
	ds_read_b128 v[20:23], v156 offset:16960
	ds_read_b128 v[8:11], v156 offset:16912
	v_pk_mul_f32 v[174:175], v[68:69], v[28:29]
	v_pk_mul_f32 v[176:177], v[68:69], v[16:17]
	v_pk_fma_f32 v[174:175], v[70:71], v[30:31], v[174:175]
	v_pk_fma_f32 v[176:177], v[70:71], v[18:19], v[176:177]
	v_add_f32_e32 v174, v174, v175
	v_add_f32_e32 v220, v176, v177
	v_pk_mul_f32 v[52:53], v[48:49], v[36:37] op_sel_hi:[0,1]
	ds_read_b128 v[16:19], v156 offset:16944
	v_add_f32_dpp v174, v174, v174 row_ror:8 row_mask:0xf bank_mask:0xf bound_ctrl:1
	v_pk_mul_f32 v[54:55], v[48:49], v[38:39] op_sel_hi:[0,1]
	v_pk_fma_f32 v[56:57], v[68:69], v[44:45], v[52:53]
	v_add_f32_dpp v174, v174, v174 row_ror:4 row_mask:0xf bank_mask:0xf bound_ctrl:1
	v_pk_fma_f32 v[58:59], v[70:71], v[46:47], v[54:55]
	v_lshl_add_u64 v[150:151], v[150:151], 0, v[64:65]
	v_add_f32_dpp v174, v174, v174 row_ror:2 row_mask:0xf bank_mask:0xf bound_ctrl:1
	v_add_u32_e32 v158, s43, v162
	v_add_u32_e32 v159, s43, v163
	v_add_f32_dpp v174, v174, v174 row_ror:1 row_mask:0xf bank_mask:0xf bound_ctrl:1
	v_add_f32_dpp v241, v233, v233 row_half_mirror row_mask:0xf bank_mask:0xf bound_ctrl:1
	v_add_f32_dpp v241, v237, v237 row_half_mirror row_mask:0xf bank_mask:0xa bound_ctrl:1
	v_pk_fma_f32 v[68:69], v[174:175], v[32:33], v[56:57] op_sel_hi:[0,1,1] neg_lo:[1,0,0] neg_hi:[1,0,0]
	v_pk_fma_f32 v[70:71], v[174:175], v[34:35], v[58:59] op_sel_hi:[0,1,1] neg_lo:[1,0,0] neg_hi:[1,0,0]
	s_waitcnt lgkmcnt(0)
	ds_read_b128 v[28:31], v156 offset:18304
	ds_read_b128 v[36:39], v156 offset:18336
	ds_read_u16_d16_hi v48, v157 offset:18304
	ds_read_b128 v[44:47], v156 offset:18368
	ds_read_b128 v[32:35], v156 offset:18320
	v_pk_mul_f32 v[172:173], v[68:69], v[4:5]
	v_pk_mul_f32 v[178:179], v[68:69], v[40:41]
	v_pk_fma_f32 v[172:173], v[70:71], v[6:7], v[172:173]
	v_pk_fma_f32 v[178:179], v[70:71], v[42:43], v[178:179]
	v_add_f32_e32 v172, v172, v173
	v_add_f32_e32 v221, v178, v179
	v_pk_mul_f32 v[52:53], v[24:25], v[12:13] op_sel_hi:[0,1]
	ds_read_b128 v[40:43], v156 offset:18352
	v_add_f32_dpp v172, v172, v172 row_ror:8 row_mask:0xf bank_mask:0xf bound_ctrl:1
	v_pk_mul_f32 v[54:55], v[24:25], v[14:15] op_sel_hi:[0,1]
	v_pk_fma_f32 v[56:57], v[68:69], v[20:21], v[52:53]
	v_add_f32_dpp v172, v172, v172 row_ror:4 row_mask:0xf bank_mask:0xf bound_ctrl:1
	v_pk_fma_f32 v[58:59], v[70:71], v[22:23], v[54:55]
	v_add_f32_dpp v242, v238, v238 quad_perm:[3,2,1,0] row_mask:0xf bank_mask:0xf bound_ctrl:1
	v_add_f32_dpp v172, v172, v172 row_ror:2 row_mask:0xf bank_mask:0xf bound_ctrl:1
	v_add_f32_dpp v243, v240, v240 quad_perm:[3,2,1,0] row_mask:0xf bank_mask:0xf bound_ctrl:1
	v_cndmask_b32_e64 v244, v242, v243, s[4:5]
	v_add_f32_dpp v172, v172, v172 row_ror:1 row_mask:0xf bank_mask:0xf bound_ctrl:1
	v_pk_fma_f32 v[68:69], v[172:173], v[8:9], v[56:57] op_sel_hi:[0,1,1] neg_lo:[1,0,0] neg_hi:[1,0,0]
	v_pk_fma_f32 v[70:71], v[172:173], v[10:11], v[58:59] op_sel_hi:[0,1,1] neg_lo:[1,0,0] neg_hi:[1,0,0]
	s_waitcnt lgkmcnt(0)
	ds_read_b128 v[4:7], v156 offset:19712
	ds_read_b128 v[12:15], v156 offset:19744
	ds_read_u16_d16_hi v24, v157 offset:19712
	ds_read_b128 v[20:23], v156 offset:19776
	ds_read_b128 v[8:11], v156 offset:19728
	v_pk_mul_f32 v[174:175], v[68:69], v[28:29]
	v_pk_mul_f32 v[176:177], v[68:69], v[16:17]
	v_pk_fma_f32 v[174:175], v[70:71], v[30:31], v[174:175]
	v_pk_fma_f32 v[176:177], v[70:71], v[18:19], v[176:177]
	v_add_f32_e32 v174, v174, v175
	v_add_f32_e32 v222, v176, v177
	v_pk_mul_f32 v[52:53], v[48:49], v[36:37] op_sel_hi:[0,1]
	ds_read_b128 v[16:19], v156 offset:19760
	v_add_f32_dpp v174, v174, v174 row_ror:8 row_mask:0xf bank_mask:0xf bound_ctrl:1
	v_pk_mul_f32 v[54:55], v[48:49], v[38:39] op_sel_hi:[0,1]
	v_pk_fma_f32 v[56:57], v[68:69], v[44:45], v[52:53]
	v_add_f32_dpp v174, v174, v174 row_ror:4 row_mask:0xf bank_mask:0xf bound_ctrl:1
	v_pk_fma_f32 v[58:59], v[70:71], v[46:47], v[54:55]
	v_add_f32_dpp v242, v239, v239 quad_perm:[3,2,1,0] row_mask:0xf bank_mask:0xf bound_ctrl:1
	v_add_f32_dpp v174, v174, v174 row_ror:2 row_mask:0xf bank_mask:0xf bound_ctrl:1
	v_add_f32_dpp v243, v241, v241 quad_perm:[3,2,1,0] row_mask:0xf bank_mask:0xf bound_ctrl:1
	s_nop 0
	v_add_f32_dpp v174, v174, v174 row_ror:1 row_mask:0xf bank_mask:0xf bound_ctrl:1
	v_pk_fma_f32 v[68:69], v[174:175], v[32:33], v[56:57] op_sel_hi:[0,1,1] neg_lo:[1,0,0] neg_hi:[1,0,0]
	v_pk_fma_f32 v[70:71], v[174:175], v[34:35], v[58:59] op_sel_hi:[0,1,1] neg_lo:[1,0,0] neg_hi:[1,0,0]
	s_waitcnt lgkmcnt(0)
; DEVI void rw_chain_task(const Params& p, int l, int seq, int head, int quarter, char* smem) {
;     ...
;     for (int c = 0; c < nch; c += 4) {
;       lds_barrier();
;       RW_STORE(R1, B1);
;       RW_LOAD(R1, c + 5);
;       RW_COMPUTE(B0, c);
;       lds_barrier();
;       RW_STORE(R2, B0);
;       RW_LOAD(R2, c + 6);
;       RW_COMPUTE(B1, c + 1);
;       lds_barrier();
;       RW_STORE(R3, B1);
;       RW_LOAD(R3, c + 7);
;       RW_COMPUTE(B0, c + 2);
;       lds_barrier();
;       RW_STORE(R0, B0);
;       RW_LOAD(R0, c + 8);
;       RW_COMPUTE(B1, c + 3);
;     }
	ds_read_b128 v[28:31], v156 offset:21120
	ds_read_b128 v[36:39], v156 offset:21152
	ds_read_u16_d16_hi v48, v157 offset:21120
	ds_read_b128 v[44:47], v156 offset:21184
	ds_read_b128 v[32:35], v156 offset:21136
	v_pk_mul_f32 v[172:173], v[68:69], v[4:5]
	v_pk_mul_f32 v[178:179], v[68:69], v[40:41]
	v_pk_fma_f32 v[172:173], v[70:71], v[6:7], v[172:173]
	v_pk_fma_f32 v[178:179], v[70:71], v[42:43], v[178:179]
	v_add_f32_e32 v172, v172, v173
	v_add_f32_e32 v223, v178, v179
	v_pk_mul_f32 v[52:53], v[24:25], v[12:13] op_sel_hi:[0,1]
	ds_read_b128 v[40:43], v156 offset:21168
	v_add_f32_dpp v172, v172, v172 row_ror:8 row_mask:0xf bank_mask:0xf bound_ctrl:1
	v_pk_mul_f32 v[54:55], v[24:25], v[14:15] op_sel_hi:[0,1]
	v_pk_fma_f32 v[56:57], v[68:69], v[20:21], v[52:53]
	v_add_f32_dpp v172, v172, v172 row_ror:4 row_mask:0xf bank_mask:0xf bound_ctrl:1
	v_pk_fma_f32 v[58:59], v[70:71], v[22:23], v[54:55]
	v_cndmask_b32_e64 v245, v242, v243, s[4:5]
	v_add_f32_dpp v172, v172, v172 row_ror:2 row_mask:0xf bank_mask:0xf bound_ctrl:1
	v_add_f32_dpp v242, v244, v244 quad_perm:[1,0,3,2] row_mask:0xf bank_mask:0xf bound_ctrl:1
	s_nop 0
	v_add_f32_dpp v172, v172, v172 row_ror:1 row_mask:0xf bank_mask:0xf bound_ctrl:1
	v_pk_fma_f32 v[68:69], v[172:173], v[8:9], v[56:57] op_sel_hi:[0,1,1] neg_lo:[1,0,0] neg_hi:[1,0,0]
	v_pk_fma_f32 v[70:71], v[172:173], v[10:11], v[58:59] op_sel_hi:[0,1,1] neg_lo:[1,0,0] neg_hi:[1,0,0]
	s_waitcnt lgkmcnt(0)
	ds_read_b128 v[4:7], v158 offset:0
	ds_read_b128 v[12:15], v158 offset:32
	ds_read_u16_d16_hi v24, v159 offset:0
	ds_read_b128 v[20:23], v158 offset:64
	ds_read_b128 v[8:11], v158 offset:16
	v_pk_mul_f32 v[174:175], v[68:69], v[28:29]
	v_pk_mul_f32 v[176:177], v[68:69], v[16:17]
	v_pk_fma_f32 v[174:175], v[70:71], v[30:31], v[174:175]
	v_pk_fma_f32 v[176:177], v[70:71], v[18:19], v[176:177]
	v_add_f32_e32 v174, v174, v175
	v_add_f32_e32 v224, v176, v177
	v_pk_mul_f32 v[52:53], v[48:49], v[36:37] op_sel_hi:[0,1]
	ds_read_b128 v[16:19], v158 offset:48
	v_add_f32_dpp v174, v174, v174 row_ror:8 row_mask:0xf bank_mask:0xf bound_ctrl:1
	v_pk_mul_f32 v[54:55], v[48:49], v[38:39] op_sel_hi:[0,1]
	v_pk_fma_f32 v[56:57], v[68:69], v[44:45], v[52:53]
	v_add_f32_dpp v174, v174, v174 row_ror:4 row_mask:0xf bank_mask:0xf bound_ctrl:1
	v_pk_fma_f32 v[58:59], v[70:71], v[46:47], v[54:55]
	v_add_f32_dpp v243, v245, v245 quad_perm:[1,0,3,2] row_mask:0xf bank_mask:0xf bound_ctrl:1
	v_add_f32_dpp v174, v174, v174 row_ror:2 row_mask:0xf bank_mask:0xf bound_ctrl:1
	v_cndmask_b32_e64 v246, v242, v243, s[6:7]
	v_bfe_u32 v61, v246, 16, 1
	v_add3_u32 v61, v246, v61, s33
	global_store_short_d16_hi v[160:161], v61, off
	v_lshl_add_u64 v[160:161], v[160:161], 0, s[46:47]
	v_add_f32_dpp v174, v174, v174 row_ror:1 row_mask:0xf bank_mask:0xf bound_ctrl:1
	v_pk_fma_f32 v[68:69], v[174:175], v[32:33], v[56:57] op_sel_hi:[0,1,1] neg_lo:[1,0,0] neg_hi:[1,0,0]
	v_pk_fma_f32 v[70:71], v[174:175], v[34:35], v[58:59] op_sel_hi:[0,1,1] neg_lo:[1,0,0] neg_hi:[1,0,0]
	s_waitcnt lgkmcnt(0)
	s_barrier
	s_mov_b32 vcc_lo, s42
	s_mov_b32 s42, s43
	s_mov_b32 s43, s45
	s_mov_b32 s45, vcc_lo
	v_add_u32_e32 v156, s42, v162
	v_add_u32_e32 v157, s42, v163
	v_add_u32_e32 v155, s45, v164
	v_add_u32_e32 v165, s45, v167
	v_add_u32_e32 v166, s45, v168
	s_waitcnt lgkmcnt(0)
	ds_read_b128 v[28:31], v156 offset:1408
	ds_read_b128 v[36:39], v156 offset:1440
	ds_read_u16_d16_hi v48, v157 offset:1408
	ds_read_b128 v[44:47], v156 offset:1472
	ds_read_b128 v[32:35], v156 offset:1424
	v_pk_mul_f32 v[172:173], v[68:69], v[4:5]
	v_pk_mul_f32 v[178:179], v[68:69], v[40:41]
	v_pk_fma_f32 v[172:173], v[70:71], v[6:7], v[172:173]
	v_pk_fma_f32 v[178:179], v[70:71], v[42:43], v[178:179]
	v_add_f32_e32 v172, v172, v173
	v_add_f32_e32 v225, v178, v179
	v_pk_mul_f32 v[52:53], v[24:25], v[12:13] op_sel_hi:[0,1]
	ds_read_b128 v[40:43], v156 offset:1456
	v_add_f32_dpp v172, v172, v172 row_ror:8 row_mask:0xf bank_mask:0xf bound_ctrl:1
	v_pk_mul_f32 v[54:55], v[24:25], v[14:15] op_sel_hi:[0,1]
	v_pk_fma_f32 v[56:57], v[68:69], v[20:21], v[52:53]
	v_add_f32_dpp v172, v172, v172 row_ror:4 row_mask:0xf bank_mask:0xf bound_ctrl:1
	v_pk_fma_f32 v[58:59], v[70:71], v[22:23], v[54:55]
	s_nop 0
	v_add_f32_dpp v172, v172, v172 row_ror:2 row_mask:0xf bank_mask:0xf bound_ctrl:1
	s_nop 1
	v_add_f32_dpp v172, v172, v172 row_ror:1 row_mask:0xf bank_mask:0xf bound_ctrl:1
	v_pk_fma_f32 v[68:69], v[172:173], v[8:9], v[56:57] op_sel_hi:[0,1,1] neg_lo:[1,0,0] neg_hi:[1,0,0]
	v_pk_fma_f32 v[70:71], v[172:173], v[10:11], v[58:59] op_sel_hi:[0,1,1] neg_lo:[1,0,0] neg_hi:[1,0,0]
	s_waitcnt lgkmcnt(0)
	ds_read_b128 v[4:7], v156 offset:2816
	ds_read_b128 v[12:15], v156 offset:2848
	ds_read_u16_d16_hi v24, v157 offset:2816
	ds_read_b128 v[20:23], v156 offset:2880
	ds_read_b128 v[8:11], v156 offset:2832
	v_pk_mul_f32 v[174:175], v[68:69], v[28:29]
	v_pk_mul_f32 v[176:177], v[68:69], v[16:17]
	v_pk_fma_f32 v[174:175], v[70:71], v[30:31], v[174:175]
	v_pk_fma_f32 v[176:177], v[70:71], v[18:19], v[176:177]
	v_add_f32_e32 v174, v174, v175
	v_add_f32_e32 v180, v176, v177
	v_pk_mul_f32 v[52:53], v[48:49], v[36:37] op_sel_hi:[0,1]
	ds_read_b128 v[16:19], v156 offset:2864
	v_add_f32_dpp v174, v174, v174 row_ror:8 row_mask:0xf bank_mask:0xf bound_ctrl:1
	v_pk_mul_f32 v[54:55], v[48:49], v[38:39] op_sel_hi:[0,1]
	v_pk_fma_f32 v[56:57], v[68:69], v[44:45], v[52:53]
	v_add_f32_dpp v174, v174, v174 row_ror:4 row_mask:0xf bank_mask:0xf bound_ctrl:1
	v_pk_fma_f32 v[58:59], v[70:71], v[46:47], v[54:55]
	s_waitcnt vmcnt(12)
	v_add_f32_dpp v174, v174, v174 row_ror:2 row_mask:0xf bank_mask:0xf bound_ctrl:1
	v_lshlrev_b32_e32 v136, 16, v72
	v_and_b32_e32 v137, 0xffff0000, v72
	v_add_f32_dpp v174, v174, v174 row_ror:1 row_mask:0xf bank_mask:0xf bound_ctrl:1
	v_add_f32_dpp v230, v196, v196 row_mirror row_mask:0xf bank_mask:0xf bound_ctrl:1
	v_add_f32_dpp v230, v212, v212 row_mirror row_mask:0xf bank_mask:0xc bound_ctrl:1
	v_pk_fma_f32 v[68:69], v[174:175], v[32:33], v[56:57] op_sel_hi:[0,1,1] neg_lo:[1,0,0] neg_hi:[1,0,0]
	v_pk_fma_f32 v[70:71], v[174:175], v[34:35], v[58:59] op_sel_hi:[0,1,1] neg_lo:[1,0,0] neg_hi:[1,0,0]
	s_waitcnt lgkmcnt(0)
	ds_read_b128 v[28:31], v156 offset:4224
	ds_read_b128 v[36:39], v156 offset:4256
	ds_read_u16_d16_hi v48, v157 offset:4224
	ds_read_b128 v[44:47], v156 offset:4288
	ds_read_b128 v[32:35], v156 offset:4240
	v_pk_mul_f32 v[172:173], v[68:69], v[4:5]
	v_pk_mul_f32 v[178:179], v[68:69], v[40:41]
	v_pk_fma_f32 v[172:173], v[70:71], v[6:7], v[172:173]
	v_pk_fma_f32 v[178:179], v[70:71], v[42:43], v[178:179]
	v_add_f32_e32 v172, v172, v173
	v_add_f32_e32 v181, v178, v179
	v_pk_mul_f32 v[52:53], v[24:25], v[12:13] op_sel_hi:[0,1]
	ds_read_b128 v[40:43], v156 offset:4272
	v_add_f32_dpp v172, v172, v172 row_ror:8 row_mask:0xf bank_mask:0xf bound_ctrl:1
	v_pk_mul_f32 v[54:55], v[24:25], v[14:15] op_sel_hi:[0,1]
	v_pk_fma_f32 v[56:57], v[68:69], v[20:21], v[52:53]
	v_add_f32_dpp v172, v172, v172 row_ror:4 row_mask:0xf bank_mask:0xf bound_ctrl:1
	v_pk_fma_f32 v[58:59], v[70:71], v[22:23], v[54:55]
	v_lshlrev_b32_e32 v138, 16, v73
	v_add_f32_dpp v172, v172, v172 row_ror:2 row_mask:0xf bank_mask:0xf bound_ctrl:1
	v_and_b32_e32 v139, 0xffff0000, v73
	v_lshlrev_b32_e32 v140, 16, v74
	v_add_f32_dpp v172, v172, v172 row_ror:1 row_mask:0xf bank_mask:0xf bound_ctrl:1
	v_add_f32_dpp v231, v197, v197 row_mirror row_mask:0xf bank_mask:0xf bound_ctrl:1
	v_add_f32_dpp v231, v213, v213 row_mirror row_mask:0xf bank_mask:0xc bound_ctrl:1
	v_pk_fma_f32 v[68:69], v[172:173], v[8:9], v[56:57] op_sel_hi:[0,1,1] neg_lo:[1,0,0] neg_hi:[1,0,0]
	v_pk_fma_f32 v[70:71], v[172:173], v[10:11], v[58:59] op_sel_hi:[0,1,1] neg_lo:[1,0,0] neg_hi:[1,0,0]
	s_waitcnt lgkmcnt(0)
	ds_read_b128 v[4:7], v156 offset:5632
	ds_read_b128 v[12:15], v156 offset:5664
	ds_read_u16_d16_hi v24, v157 offset:5632
	ds_read_b128 v[20:23], v156 offset:5696
	ds_read_b128 v[8:11], v156 offset:5648
	v_pk_mul_f32 v[174:175], v[68:69], v[28:29]
	v_pk_mul_f32 v[176:177], v[68:69], v[16:17]
	v_pk_fma_f32 v[174:175], v[70:71], v[30:31], v[174:175]
	v_pk_fma_f32 v[176:177], v[70:71], v[18:19], v[176:177]
	v_add_f32_e32 v174, v174, v175
	v_add_f32_e32 v182, v176, v177
	v_pk_mul_f32 v[52:53], v[48:49], v[36:37] op_sel_hi:[0,1]
	ds_read_b128 v[16:19], v156 offset:5680
	v_add_f32_dpp v174, v174, v174 row_ror:8 row_mask:0xf bank_mask:0xf bound_ctrl:1
	v_pk_mul_f32 v[54:55], v[48:49], v[38:39] op_sel_hi:[0,1]
	v_pk_fma_f32 v[56:57], v[68:69], v[44:45], v[52:53]
	v_add_f32_dpp v174, v174, v174 row_ror:4 row_mask:0xf bank_mask:0xf bound_ctrl:1
	v_pk_fma_f32 v[58:59], v[70:71], v[46:47], v[54:55]
	v_and_b32_e32 v141, 0xffff0000, v74
	v_add_f32_dpp v174, v174, v174 row_ror:2 row_mask:0xf bank_mask:0xf bound_ctrl:1
	v_lshlrev_b32_e32 v142, 16, v75
	v_and_b32_e32 v143, 0xffff0000, v75
	v_add_f32_dpp v174, v174, v174 row_ror:1 row_mask:0xf bank_mask:0xf bound_ctrl:1
	v_add_f32_dpp v232, v198, v198 row_mirror row_mask:0xf bank_mask:0xf bound_ctrl:1
	v_add_f32_dpp v232, v220, v220 row_mirror row_mask:0xf bank_mask:0xc bound_ctrl:1
	v_pk_fma_f32 v[68:69], v[174:175], v[32:33], v[56:57] op_sel_hi:[0,1,1] neg_lo:[1,0,0] neg_hi:[1,0,0]
	v_pk_fma_f32 v[70:71], v[174:175], v[34:35], v[58:59] op_sel_hi:[0,1,1] neg_lo:[1,0,0] neg_hi:[1,0,0]
	s_waitcnt lgkmcnt(0)
	ds_read_b128 v[28:31], v156 offset:7040
	ds_read_b128 v[36:39], v156 offset:7072
	ds_read_u16_d16_hi v48, v157 offset:7040
	ds_read_b128 v[44:47], v156 offset:7104
	ds_read_b128 v[32:35], v156 offset:7056
	v_pk_mul_f32 v[172:173], v[68:69], v[4:5]
	v_pk_mul_f32 v[178:179], v[68:69], v[40:41]
	v_pk_fma_f32 v[172:173], v[70:71], v[6:7], v[172:173]
	v_pk_fma_f32 v[178:179], v[70:71], v[42:43], v[178:179]
	v_add_f32_e32 v172, v172, v173
	v_add_f32_e32 v183, v178, v179
	v_pk_mul_f32 v[52:53], v[24:25], v[12:13] op_sel_hi:[0,1]
	ds_read_b128 v[40:43], v156 offset:7088
	v_add_f32_dpp v172, v172, v172 row_ror:8 row_mask:0xf bank_mask:0xf bound_ctrl:1
	v_pk_mul_f32 v[54:55], v[24:25], v[14:15] op_sel_hi:[0,1]
	v_pk_fma_f32 v[56:57], v[68:69], v[20:21], v[52:53]
	v_add_f32_dpp v172, v172, v172 row_ror:4 row_mask:0xf bank_mask:0xf bound_ctrl:1
	v_pk_fma_f32 v[58:59], v[70:71], v[22:23], v[54:55]
	ds_write_b128 v155, v[136:139] offset:0
	v_add_f32_dpp v172, v172, v172 row_ror:2 row_mask:0xf bank_mask:0xf bound_ctrl:1
	ds_write_b128 v155, v[140:143] offset:80
	v_lshlrev_b32_e32 v136, 16, v76
	v_add_f32_dpp v172, v172, v172 row_ror:1 row_mask:0xf bank_mask:0xf bound_ctrl:1
	v_add_f32_dpp v233, v199, v199 row_mirror row_mask:0xf bank_mask:0xf bound_ctrl:1
	v_add_f32_dpp v233, v221, v221 row_mirror row_mask:0xf bank_mask:0xc bound_ctrl:1
	v_pk_fma_f32 v[68:69], v[172:173], v[8:9], v[56:57] op_sel_hi:[0,1,1] neg_lo:[1,0,0] neg_hi:[1,0,0]
	v_pk_fma_f32 v[70:71], v[172:173], v[10:11], v[58:59] op_sel_hi:[0,1,1] neg_lo:[1,0,0] neg_hi:[1,0,0]
	v_add_f32_dpp v234, v200, v200 row_mirror row_mask:0xf bank_mask:0xf bound_ctrl:1
	s_waitcnt lgkmcnt(2)
	ds_read_b128 v[4:7], v156 offset:8448
	ds_read_b128 v[12:15], v156 offset:8480
	ds_read_u16_d16_hi v24, v157 offset:8448
	ds_read_b128 v[20:23], v156 offset:8512
	ds_read_b128 v[8:11], v156 offset:8464
	v_pk_mul_f32 v[174:175], v[68:69], v[28:29]
	v_pk_mul_f32 v[176:177], v[68:69], v[16:17]
	v_pk_fma_f32 v[174:175], v[70:71], v[30:31], v[174:175]
	v_pk_fma_f32 v[176:177], v[70:71], v[18:19], v[176:177]
	v_add_f32_e32 v174, v174, v175
	v_add_f32_e32 v184, v176, v177
	v_pk_mul_f32 v[52:53], v[48:49], v[36:37] op_sel_hi:[0,1]
	ds_read_b128 v[16:19], v156 offset:8496
	v_add_f32_dpp v174, v174, v174 row_ror:8 row_mask:0xf bank_mask:0xf bound_ctrl:1
	v_pk_mul_f32 v[54:55], v[48:49], v[38:39] op_sel_hi:[0,1]
	v_pk_fma_f32 v[56:57], v[68:69], v[44:45], v[52:53]
	v_add_f32_dpp v174, v174, v174 row_ror:4 row_mask:0xf bank_mask:0xf bound_ctrl:1
	v_pk_fma_f32 v[58:59], v[70:71], v[46:47], v[54:55]
	v_and_b32_e32 v137, 0xffff0000, v76
	v_add_f32_dpp v174, v174, v174 row_ror:2 row_mask:0xf bank_mask:0xf bound_ctrl:1
	v_lshlrev_b32_e32 v138, 16, v77
	v_and_b32_e32 v139, 0xffff0000, v77
	v_add_f32_dpp v174, v174, v174 row_ror:1 row_mask:0xf bank_mask:0xf bound_ctrl:1
	v_add_f32_dpp v234, v222, v222 row_mirror row_mask:0xf bank_mask:0xc bound_ctrl:1
	v_add_f32_dpp v235, v201, v201 row_mirror row_mask:0xf bank_mask:0xf bound_ctrl:1
	v_pk_fma_f32 v[68:69], v[174:175], v[32:33], v[56:57] op_sel_hi:[0,1,1] neg_lo:[1,0,0] neg_hi:[1,0,0]
	v_pk_fma_f32 v[70:71], v[174:175], v[34:35], v[58:59] op_sel_hi:[0,1,1] neg_lo:[1,0,0] neg_hi:[1,0,0]
	s_waitcnt lgkmcnt(0)
	ds_read_b128 v[28:31], v156 offset:9856
	ds_read_b128 v[36:39], v156 offset:9888
	ds_read_u16_d16_hi v48, v157 offset:9856
	ds_read_b128 v[44:47], v156 offset:9920
	ds_read_b128 v[32:35], v156 offset:9872
	v_pk_mul_f32 v[172:173], v[68:69], v[4:5]
	v_pk_mul_f32 v[178:179], v[68:69], v[40:41]
	v_pk_fma_f32 v[172:173], v[70:71], v[6:7], v[172:173]
	v_pk_fma_f32 v[178:179], v[70:71], v[42:43], v[178:179]
	v_add_f32_e32 v172, v172, v173
	v_add_f32_e32 v185, v178, v179
	v_pk_mul_f32 v[52:53], v[24:25], v[12:13] op_sel_hi:[0,1]
	ds_read_b128 v[40:43], v156 offset:9904
	v_add_f32_dpp v172, v172, v172 row_ror:8 row_mask:0xf bank_mask:0xf bound_ctrl:1
	v_pk_mul_f32 v[54:55], v[24:25], v[14:15] op_sel_hi:[0,1]
	v_pk_fma_f32 v[56:57], v[68:69], v[20:21], v[52:53]
	v_add_f32_dpp v172, v172, v172 row_ror:4 row_mask:0xf bank_mask:0xf bound_ctrl:1
	v_pk_fma_f32 v[58:59], v[70:71], v[22:23], v[54:55]
	v_lshlrev_b32_e32 v140, 16, v78
	v_add_f32_dpp v172, v172, v172 row_ror:2 row_mask:0xf bank_mask:0xf bound_ctrl:1
	v_and_b32_e32 v141, 0xffff0000, v78
	v_lshlrev_b32_e32 v142, 16, v79
	v_add_f32_dpp v172, v172, v172 row_ror:1 row_mask:0xf bank_mask:0xf bound_ctrl:1
	v_add_f32_dpp v235, v223, v223 row_mirror row_mask:0xf bank_mask:0xc bound_ctrl:1
	v_add_f32_dpp v236, v210, v210 row_mirror row_mask:0xf bank_mask:0xf bound_ctrl:1
	v_pk_fma_f32 v[68:69], v[172:173], v[8:9], v[56:57] op_sel_hi:[0,1,1] neg_lo:[1,0,0] neg_hi:[1,0,0]
	v_pk_fma_f32 v[70:71], v[172:173], v[10:11], v[58:59] op_sel_hi:[0,1,1] neg_lo:[1,0,0] neg_hi:[1,0,0]
	s_waitcnt lgkmcnt(0)
	ds_read_b128 v[4:7], v156 offset:11264
	ds_read_b128 v[12:15], v156 offset:11296
	ds_read_u16_d16_hi v24, v157 offset:11264
	ds_read_b128 v[20:23], v156 offset:11328
	ds_read_b128 v[8:11], v156 offset:11280
	v_pk_mul_f32 v[174:175], v[68:69], v[28:29]
	v_pk_mul_f32 v[176:177], v[68:69], v[16:17]
	v_pk_fma_f32 v[174:175], v[70:71], v[30:31], v[174:175]
	v_pk_fma_f32 v[176:177], v[70:71], v[18:19], v[176:177]
	v_add_f32_e32 v174, v174, v175
	v_add_f32_e32 v186, v176, v177
	v_pk_mul_f32 v[52:53], v[48:49], v[36:37] op_sel_hi:[0,1]
	ds_read_b128 v[16:19], v156 offset:11312
	v_add_f32_dpp v174, v174, v174 row_ror:8 row_mask:0xf bank_mask:0xf bound_ctrl:1
	v_pk_mul_f32 v[54:55], v[48:49], v[38:39] op_sel_hi:[0,1]
	v_pk_fma_f32 v[56:57], v[68:69], v[44:45], v[52:53]
	v_add_f32_dpp v174, v174, v174 row_ror:4 row_mask:0xf bank_mask:0xf bound_ctrl:1
	v_pk_fma_f32 v[58:59], v[70:71], v[46:47], v[54:55]
	v_and_b32_e32 v143, 0xffff0000, v79
	v_add_f32_dpp v174, v174, v174 row_ror:2 row_mask:0xf bank_mask:0xf bound_ctrl:1
	ds_write_b128 v155, v[136:139] offset:11264
	ds_write_b128 v155, v[140:143] offset:11344
	v_add_f32_dpp v174, v174, v174 row_ror:1 row_mask:0xf bank_mask:0xf bound_ctrl:1
	v_add_f32_dpp v236, v224, v224 row_mirror row_mask:0xf bank_mask:0xc bound_ctrl:1
	v_add_f32_dpp v237, v211, v211 row_mirror row_mask:0xf bank_mask:0xf bound_ctrl:1
	v_pk_fma_f32 v[68:69], v[174:175], v[32:33], v[56:57] op_sel_hi:[0,1,1] neg_lo:[1,0,0] neg_hi:[1,0,0]
	v_pk_fma_f32 v[70:71], v[174:175], v[34:35], v[58:59] op_sel_hi:[0,1,1] neg_lo:[1,0,0] neg_hi:[1,0,0]
	s_waitcnt lgkmcnt(2)
	ds_read_b128 v[28:31], v156 offset:12672
	ds_read_b128 v[36:39], v156 offset:12704
	ds_read_u16_d16_hi v48, v157 offset:12672
	ds_read_b128 v[44:47], v156 offset:12736
	ds_read_b128 v[32:35], v156 offset:12688
	v_pk_mul_f32 v[172:173], v[68:69], v[4:5]
	v_pk_mul_f32 v[178:179], v[68:69], v[40:41]
	v_pk_fma_f32 v[172:173], v[70:71], v[6:7], v[172:173]
	v_pk_fma_f32 v[178:179], v[70:71], v[42:43], v[178:179]
	v_add_f32_e32 v172, v172, v173
	v_add_f32_e32 v187, v178, v179
	v_pk_mul_f32 v[52:53], v[24:25], v[12:13] op_sel_hi:[0,1]
	ds_read_b128 v[40:43], v156 offset:12720
	v_add_f32_dpp v172, v172, v172 row_ror:8 row_mask:0xf bank_mask:0xf bound_ctrl:1
	v_pk_mul_f32 v[54:55], v[24:25], v[14:15] op_sel_hi:[0,1]
	v_pk_fma_f32 v[56:57], v[68:69], v[20:21], v[52:53]
	v_add_f32_dpp v172, v172, v172 row_ror:4 row_mask:0xf bank_mask:0xf bound_ctrl:1
	v_pk_fma_f32 v[58:59], v[70:71], v[22:23], v[54:55]
	ds_write_b128 v165, v[80:83]
	v_add_f32_dpp v172, v172, v172 row_ror:2 row_mask:0xf bank_mask:0xf bound_ctrl:1
	ds_write_b128 v166, v[84:87]
	global_load_dwordx4 v[72:75], v[144:145], off
	v_add_f32_dpp v172, v172, v172 row_ror:1 row_mask:0xf bank_mask:0xf bound_ctrl:1
	v_add_f32_dpp v237, v225, v225 row_mirror row_mask:0xf bank_mask:0xc bound_ctrl:1
	v_add_f32_dpp v238, v230, v230 row_half_mirror row_mask:0xf bank_mask:0xf bound_ctrl:1
	v_pk_fma_f32 v[68:69], v[172:173], v[8:9], v[56:57] op_sel_hi:[0,1,1] neg_lo:[1,0,0] neg_hi:[1,0,0]
	v_pk_fma_f32 v[70:71], v[172:173], v[10:11], v[58:59] op_sel_hi:[0,1,1] neg_lo:[1,0,0] neg_hi:[1,0,0]
	v_add_f32_dpp v238, v234, v234 row_half_mirror row_mask:0xf bank_mask:0xa bound_ctrl:1
	s_waitcnt lgkmcnt(2)
	ds_read_b128 v[4:7], v156 offset:14080
	ds_read_b128 v[12:15], v156 offset:14112
	ds_read_u16_d16_hi v24, v157 offset:14080
	ds_read_b128 v[20:23], v156 offset:14144
	ds_read_b128 v[8:11], v156 offset:14096
	v_pk_mul_f32 v[174:175], v[68:69], v[28:29]
	v_pk_mul_f32 v[176:177], v[68:69], v[16:17]
	v_pk_fma_f32 v[174:175], v[70:71], v[30:31], v[174:175]
	v_pk_fma_f32 v[176:177], v[70:71], v[18:19], v[176:177]
	v_add_f32_e32 v174, v174, v175
	v_add_f32_e32 v188, v176, v177
	v_pk_mul_f32 v[52:53], v[48:49], v[36:37] op_sel_hi:[0,1]
	ds_read_b128 v[16:19], v156 offset:14128
	v_add_f32_dpp v174, v174, v174 row_ror:8 row_mask:0xf bank_mask:0xf bound_ctrl:1
	v_pk_mul_f32 v[54:55], v[48:49], v[38:39] op_sel_hi:[0,1]
	v_pk_fma_f32 v[56:57], v[68:69], v[44:45], v[52:53]
	v_add_f32_dpp v174, v174, v174 row_ror:4 row_mask:0xf bank_mask:0xf bound_ctrl:1
	v_pk_fma_f32 v[58:59], v[70:71], v[46:47], v[54:55]
	global_load_dwordx4 v[76:79], v[146:147], off
	v_add_f32_dpp v174, v174, v174 row_ror:2 row_mask:0xf bank_mask:0xf bound_ctrl:1
	global_load_dwordx4 v[80:83], v[148:149], off
	global_load_dwordx4 v[84:87], v[150:151], off
	v_add_f32_dpp v174, v174, v174 row_ror:1 row_mask:0xf bank_mask:0xf bound_ctrl:1
	v_add_f32_dpp v239, v231, v231 row_half_mirror row_mask:0xf bank_mask:0xf bound_ctrl:1
	v_add_f32_dpp v239, v235, v235 row_half_mirror row_mask:0xf bank_mask:0xa bound_ctrl:1
	v_pk_fma_f32 v[68:69], v[174:175], v[32:33], v[56:57] op_sel_hi:[0,1,1] neg_lo:[1,0,0] neg_hi:[1,0,0]
	v_pk_fma_f32 v[70:71], v[174:175], v[34:35], v[58:59] op_sel_hi:[0,1,1] neg_lo:[1,0,0] neg_hi:[1,0,0]
	s_waitcnt lgkmcnt(0)
	ds_read_b128 v[28:31], v156 offset:15488
	ds_read_b128 v[36:39], v156 offset:15520
	ds_read_u16_d16_hi v48, v157 offset:15488
	ds_read_b128 v[44:47], v156 offset:15552
	ds_read_b128 v[32:35], v156 offset:15504
	v_pk_mul_f32 v[172:173], v[68:69], v[4:5]
	v_pk_mul_f32 v[178:179], v[68:69], v[40:41]
	v_pk_fma_f32 v[172:173], v[70:71], v[6:7], v[172:173]
	v_pk_fma_f32 v[178:179], v[70:71], v[42:43], v[178:179]
	v_add_f32_e32 v172, v172, v173
	v_add_f32_e32 v189, v178, v179
	v_pk_mul_f32 v[52:53], v[24:25], v[12:13] op_sel_hi:[0,1]
	ds_read_b128 v[40:43], v156 offset:15536
	v_add_f32_dpp v172, v172, v172 row_ror:8 row_mask:0xf bank_mask:0xf bound_ctrl:1
	v_pk_mul_f32 v[54:55], v[24:25], v[14:15] op_sel_hi:[0,1]
	v_pk_fma_f32 v[56:57], v[68:69], v[20:21], v[52:53]
	v_add_f32_dpp v172, v172, v172 row_ror:4 row_mask:0xf bank_mask:0xf bound_ctrl:1
	v_pk_fma_f32 v[58:59], v[70:71], v[22:23], v[54:55]
	v_lshl_add_u64 v[144:145], v[144:145], 0, v[152:153]
	v_add_f32_dpp v172, v172, v172 row_ror:2 row_mask:0xf bank_mask:0xf bound_ctrl:1
	v_lshl_add_u64 v[146:147], v[146:147], 0, v[152:153]
	v_lshl_add_u64 v[148:149], v[148:149], 0, v[62:63]
	v_add_f32_dpp v172, v172, v172 row_ror:1 row_mask:0xf bank_mask:0xf bound_ctrl:1
	v_add_f32_dpp v240, v232, v232 row_half_mirror row_mask:0xf bank_mask:0xf bound_ctrl:1
	v_add_f32_dpp v240, v236, v236 row_half_mirror row_mask:0xf bank_mask:0xa bound_ctrl:1
	v_pk_fma_f32 v[68:69], v[172:173], v[8:9], v[56:57] op_sel_hi:[0,1,1] neg_lo:[1,0,0] neg_hi:[1,0,0]
	v_pk_fma_f32 v[70:71], v[172:173], v[10:11], v[58:59] op_sel_hi:[0,1,1] neg_lo:[1,0,0] neg_hi:[1,0,0]
	s_waitcnt lgkmcnt(0)
	ds_read_b128 v[4:7], v156 offset:16896
	ds_read_b128 v[12:15], v156 offset:16928
	ds_read_u16_d16_hi v24, v157 offset:16896
	ds_read_b128 v[20:23], v156 offset:16960
	ds_read_b128 v[8:11], v156 offset:16912
	v_pk_mul_f32 v[174:175], v[68:69], v[28:29]
	v_pk_mul_f32 v[176:177], v[68:69], v[16:17]
	v_pk_fma_f32 v[174:175], v[70:71], v[30:31], v[174:175]
	v_pk_fma_f32 v[176:177], v[70:71], v[18:19], v[176:177]
	v_add_f32_e32 v174, v174, v175
	v_add_f32_e32 v190, v176, v177
	v_pk_mul_f32 v[52:53], v[48:49], v[36:37] op_sel_hi:[0,1]
	ds_read_b128 v[16:19], v156 offset:16944
	v_add_f32_dpp v174, v174, v174 row_ror:8 row_mask:0xf bank_mask:0xf bound_ctrl:1
	v_pk_mul_f32 v[54:55], v[48:49], v[38:39] op_sel_hi:[0,1]
	v_pk_fma_f32 v[56:57], v[68:69], v[44:45], v[52:53]
	v_add_f32_dpp v174, v174, v174 row_ror:4 row_mask:0xf bank_mask:0xf bound_ctrl:1
	v_pk_fma_f32 v[58:59], v[70:71], v[46:47], v[54:55]
	v_lshl_add_u64 v[150:151], v[150:151], 0, v[64:65]
	v_add_f32_dpp v174, v174, v174 row_ror:2 row_mask:0xf bank_mask:0xf bound_ctrl:1
	v_add_u32_e32 v158, s43, v162
	v_add_u32_e32 v159, s43, v163
	v_add_f32_dpp v174, v174, v174 row_ror:1 row_mask:0xf bank_mask:0xf bound_ctrl:1
	v_add_f32_dpp v241, v233, v233 row_half_mirror row_mask:0xf bank_mask:0xf bound_ctrl:1
	v_add_f32_dpp v241, v237, v237 row_half_mirror row_mask:0xf bank_mask:0xa bound_ctrl:1
	v_pk_fma_f32 v[68:69], v[174:175], v[32:33], v[56:57] op_sel_hi:[0,1,1] neg_lo:[1,0,0] neg_hi:[1,0,0]
	v_pk_fma_f32 v[70:71], v[174:175], v[34:35], v[58:59] op_sel_hi:[0,1,1] neg_lo:[1,0,0] neg_hi:[1,0,0]
	s_waitcnt lgkmcnt(0)
	ds_read_b128 v[28:31], v156 offset:18304
	ds_read_b128 v[36:39], v156 offset:18336
	ds_read_u16_d16_hi v48, v157 offset:18304
	ds_read_b128 v[44:47], v156 offset:18368
	ds_read_b128 v[32:35], v156 offset:18320
	v_pk_mul_f32 v[172:173], v[68:69], v[4:5]
	v_pk_mul_f32 v[178:179], v[68:69], v[40:41]
	v_pk_fma_f32 v[172:173], v[70:71], v[6:7], v[172:173]
	v_pk_fma_f32 v[178:179], v[70:71], v[42:43], v[178:179]
	v_add_f32_e32 v172, v172, v173
	v_add_f32_e32 v191, v178, v179
	v_pk_mul_f32 v[52:53], v[24:25], v[12:13] op_sel_hi:[0,1]
	ds_read_b128 v[40:43], v156 offset:18352
	v_add_f32_dpp v172, v172, v172 row_ror:8 row_mask:0xf bank_mask:0xf bound_ctrl:1
	v_pk_mul_f32 v[54:55], v[24:25], v[14:15] op_sel_hi:[0,1]
	v_pk_fma_f32 v[56:57], v[68:69], v[20:21], v[52:53]
	v_add_f32_dpp v172, v172, v172 row_ror:4 row_mask:0xf bank_mask:0xf bound_ctrl:1
	v_pk_fma_f32 v[58:59], v[70:71], v[22:23], v[54:55]
	v_add_f32_dpp v242, v238, v238 quad_perm:[3,2,1,0] row_mask:0xf bank_mask:0xf bound_ctrl:1
	v_add_f32_dpp v172, v172, v172 row_ror:2 row_mask:0xf bank_mask:0xf bound_ctrl:1
	v_add_f32_dpp v243, v240, v240 quad_perm:[3,2,1,0] row_mask:0xf bank_mask:0xf bound_ctrl:1
	v_cndmask_b32_e64 v244, v242, v243, s[4:5]
	v_add_f32_dpp v172, v172, v172 row_ror:1 row_mask:0xf bank_mask:0xf bound_ctrl:1
	v_pk_fma_f32 v[68:69], v[172:173], v[8:9], v[56:57] op_sel_hi:[0,1,1] neg_lo:[1,0,0] neg_hi:[1,0,0]
	v_pk_fma_f32 v[70:71], v[172:173], v[10:11], v[58:59] op_sel_hi:[0,1,1] neg_lo:[1,0,0] neg_hi:[1,0,0]
	s_waitcnt lgkmcnt(0)
	ds_read_b128 v[4:7], v156 offset:19712
	ds_read_b128 v[12:15], v156 offset:19744
	ds_read_u16_d16_hi v24, v157 offset:19712
	ds_read_b128 v[20:23], v156 offset:19776
	ds_read_b128 v[8:11], v156 offset:19728
	v_pk_mul_f32 v[174:175], v[68:69], v[28:29]
	v_pk_mul_f32 v[176:177], v[68:69], v[16:17]
	v_pk_fma_f32 v[174:175], v[70:71], v[30:31], v[174:175]
	v_pk_fma_f32 v[176:177], v[70:71], v[18:19], v[176:177]
	v_add_f32_e32 v174, v174, v175
	v_add_f32_e32 v192, v176, v177
	v_pk_mul_f32 v[52:53], v[48:49], v[36:37] op_sel_hi:[0,1]
	ds_read_b128 v[16:19], v156 offset:19760
	v_add_f32_dpp v174, v174, v174 row_ror:8 row_mask:0xf bank_mask:0xf bound_ctrl:1
	v_pk_mul_f32 v[54:55], v[48:49], v[38:39] op_sel_hi:[0,1]
	v_pk_fma_f32 v[56:57], v[68:69], v[44:45], v[52:53]
	v_add_f32_dpp v174, v174, v174 row_ror:4 row_mask:0xf bank_mask:0xf bound_ctrl:1
	v_pk_fma_f32 v[58:59], v[70:71], v[46:47], v[54:55]
	v_add_f32_dpp v242, v239, v239 quad_perm:[3,2,1,0] row_mask:0xf bank_mask:0xf bound_ctrl:1
	v_add_f32_dpp v174, v174, v174 row_ror:2 row_mask:0xf bank_mask:0xf bound_ctrl:1
	v_add_f32_dpp v243, v241, v241 quad_perm:[3,2,1,0] row_mask:0xf bank_mask:0xf bound_ctrl:1
	s_nop 0
	v_add_f32_dpp v174, v174, v174 row_ror:1 row_mask:0xf bank_mask:0xf bound_ctrl:1
	v_pk_fma_f32 v[68:69], v[174:175], v[32:33], v[56:57] op_sel_hi:[0,1,1] neg_lo:[1,0,0] neg_hi:[1,0,0]
	v_pk_fma_f32 v[70:71], v[174:175], v[34:35], v[58:59] op_sel_hi:[0,1,1] neg_lo:[1,0,0] neg_hi:[1,0,0]
	s_waitcnt lgkmcnt(0)
	ds_read_b128 v[28:31], v156 offset:21120
	ds_read_b128 v[36:39], v156 offset:21152
	ds_read_u16_d16_hi v48, v157 offset:21120
	ds_read_b128 v[44:47], v156 offset:21184
	ds_read_b128 v[32:35], v156 offset:21136
	v_pk_mul_f32 v[172:173], v[68:69], v[4:5]
	v_pk_mul_f32 v[178:179], v[68:69], v[40:41]
	v_pk_fma_f32 v[172:173], v[70:71], v[6:7], v[172:173]
	v_pk_fma_f32 v[178:179], v[70:71], v[42:43], v[178:179]
	v_add_f32_e32 v172, v172, v173
	v_add_f32_e32 v193, v178, v179
	v_pk_mul_f32 v[52:53], v[24:25], v[12:13] op_sel_hi:[0,1]
	ds_read_b128 v[40:43], v156 offset:21168
	v_add_f32_dpp v172, v172, v172 row_ror:8 row_mask:0xf bank_mask:0xf bound_ctrl:1
	v_pk_mul_f32 v[54:55], v[24:25], v[14:15] op_sel_hi:[0,1]
	v_pk_fma_f32 v[56:57], v[68:69], v[20:21], v[52:53]
	v_add_f32_dpp v172, v172, v172 row_ror:4 row_mask:0xf bank_mask:0xf bound_ctrl:1
	v_pk_fma_f32 v[58:59], v[70:71], v[22:23], v[54:55]
	v_cndmask_b32_e64 v245, v242, v243, s[4:5]
	v_add_f32_dpp v172, v172, v172 row_ror:2 row_mask:0xf bank_mask:0xf bound_ctrl:1
	v_add_f32_dpp v242, v244, v244 quad_perm:[1,0,3,2] row_mask:0xf bank_mask:0xf bound_ctrl:1
	s_nop 0
	v_add_f32_dpp v172, v172, v172 row_ror:1 row_mask:0xf bank_mask:0xf bound_ctrl:1
	v_pk_fma_f32 v[68:69], v[172:173], v[8:9], v[56:57] op_sel_hi:[0,1,1] neg_lo:[1,0,0] neg_hi:[1,0,0]
	v_pk_fma_f32 v[70:71], v[172:173], v[10:11], v[58:59] op_sel_hi:[0,1,1] neg_lo:[1,0,0] neg_hi:[1,0,0]
	s_waitcnt lgkmcnt(0)
	ds_read_b128 v[4:7], v158 offset:0
	ds_read_b128 v[12:15], v158 offset:32
	ds_read_u16_d16_hi v24, v159 offset:0
	ds_read_b128 v[20:23], v158 offset:64
	ds_read_b128 v[8:11], v158 offset:16
	v_pk_mul_f32 v[174:175], v[68:69], v[28:29]
	v_pk_mul_f32 v[176:177], v[68:69], v[16:17]
	v_pk_fma_f32 v[174:175], v[70:71], v[30:31], v[174:175]
	v_pk_fma_f32 v[176:177], v[70:71], v[18:19], v[176:177]
	v_add_f32_e32 v174, v174, v175
	v_add_f32_e32 v194, v176, v177
	v_pk_mul_f32 v[52:53], v[48:49], v[36:37] op_sel_hi:[0,1]
	ds_read_b128 v[16:19], v158 offset:48
	v_add_f32_dpp v174, v174, v174 row_ror:8 row_mask:0xf bank_mask:0xf bound_ctrl:1
	v_pk_mul_f32 v[54:55], v[48:49], v[38:39] op_sel_hi:[0,1]
	v_pk_fma_f32 v[56:57], v[68:69], v[44:45], v[52:53]
	v_add_f32_dpp v174, v174, v174 row_ror:4 row_mask:0xf bank_mask:0xf bound_ctrl:1
	v_pk_fma_f32 v[58:59], v[70:71], v[46:47], v[54:55]
	v_add_f32_dpp v243, v245, v245 quad_perm:[1,0,3,2] row_mask:0xf bank_mask:0xf bound_ctrl:1
	v_add_f32_dpp v174, v174, v174 row_ror:2 row_mask:0xf bank_mask:0xf bound_ctrl:1
	v_cndmask_b32_e64 v246, v242, v243, s[6:7]
	v_bfe_u32 v61, v246, 16, 1
	v_add3_u32 v61, v246, v61, s33
	global_store_short_d16_hi v[160:161], v61, off
	v_lshl_add_u64 v[160:161], v[160:161], 0, s[46:47]
	v_add_f32_dpp v174, v174, v174 row_ror:1 row_mask:0xf bank_mask:0xf bound_ctrl:1
	v_pk_fma_f32 v[68:69], v[174:175], v[32:33], v[56:57] op_sel_hi:[0,1,1] neg_lo:[1,0,0] neg_hi:[1,0,0]
	v_pk_fma_f32 v[70:71], v[174:175], v[34:35], v[58:59] op_sel_hi:[0,1,1] neg_lo:[1,0,0] neg_hi:[1,0,0]
	s_waitcnt lgkmcnt(0)
	s_barrier
; DEVI void rw_chain_task(const Params& p, int l, int seq, int head, int quarter, char* smem) {
;     ...
;     for (int c = 0; c < nch; c += 4) {
;       lds_barrier();
;       RW_STORE(R1, B1);
;       RW_LOAD(R1, c + 5);
;       RW_COMPUTE(B0, c);
;       lds_barrier();
;       RW_STORE(R2, B0);
;       RW_LOAD(R2, c + 6);
;       RW_COMPUTE(B1, c + 1);
;       lds_barrier();
;       RW_STORE(R3, B1);
;       RW_LOAD(R3, c + 7);
;       RW_COMPUTE(B0, c + 2);
;       lds_barrier();
;       RW_STORE(R0, B0);
;       RW_LOAD(R0, c + 8);
;       RW_COMPUTE(B1, c + 3);
;     }
	s_mov_b32 vcc_lo, s42
	s_mov_b32 s42, s43
	s_mov_b32 s43, s45
	s_mov_b32 s45, vcc_lo
	v_add_u32_e32 v156, s42, v162
	v_add_u32_e32 v157, s42, v163
	v_add_u32_e32 v155, s45, v164
	v_add_u32_e32 v165, s45, v167
	v_add_u32_e32 v166, s45, v168
	s_waitcnt lgkmcnt(0)
	ds_read_b128 v[28:31], v156 offset:1408
	ds_read_b128 v[36:39], v156 offset:1440
	ds_read_u16_d16_hi v48, v157 offset:1408
	ds_read_b128 v[44:47], v156 offset:1472
	ds_read_b128 v[32:35], v156 offset:1424
	v_pk_mul_f32 v[172:173], v[68:69], v[4:5]
	v_pk_mul_f32 v[178:179], v[68:69], v[40:41]
	v_pk_fma_f32 v[172:173], v[70:71], v[6:7], v[172:173]
	v_pk_fma_f32 v[178:179], v[70:71], v[42:43], v[178:179]
	v_add_f32_e32 v172, v172, v173
	v_add_f32_e32 v195, v178, v179
	v_pk_mul_f32 v[52:53], v[24:25], v[12:13] op_sel_hi:[0,1]
	ds_read_b128 v[40:43], v156 offset:1456
	v_add_f32_dpp v172, v172, v172 row_ror:8 row_mask:0xf bank_mask:0xf bound_ctrl:1
	v_pk_mul_f32 v[54:55], v[24:25], v[14:15] op_sel_hi:[0,1]
	v_pk_fma_f32 v[56:57], v[68:69], v[20:21], v[52:53]
	v_add_f32_dpp v172, v172, v172 row_ror:4 row_mask:0xf bank_mask:0xf bound_ctrl:1
	v_pk_fma_f32 v[58:59], v[70:71], v[22:23], v[54:55]
	s_nop 0
	v_add_f32_dpp v172, v172, v172 row_ror:2 row_mask:0xf bank_mask:0xf bound_ctrl:1
	s_nop 1
	v_add_f32_dpp v172, v172, v172 row_ror:1 row_mask:0xf bank_mask:0xf bound_ctrl:1
	v_pk_fma_f32 v[68:69], v[172:173], v[8:9], v[56:57] op_sel_hi:[0,1,1] neg_lo:[1,0,0] neg_hi:[1,0,0]
	v_pk_fma_f32 v[70:71], v[172:173], v[10:11], v[58:59] op_sel_hi:[0,1,1] neg_lo:[1,0,0] neg_hi:[1,0,0]
	s_waitcnt lgkmcnt(0)
	ds_read_b128 v[4:7], v156 offset:2816
	ds_read_b128 v[12:15], v156 offset:2848
	ds_read_u16_d16_hi v24, v157 offset:2816
	ds_read_b128 v[20:23], v156 offset:2880
	ds_read_b128 v[8:11], v156 offset:2832
	v_pk_mul_f32 v[174:175], v[68:69], v[28:29]
	v_pk_mul_f32 v[176:177], v[68:69], v[16:17]
	v_pk_fma_f32 v[174:175], v[70:71], v[30:31], v[174:175]
	v_pk_fma_f32 v[176:177], v[70:71], v[18:19], v[176:177]
	v_add_f32_e32 v174, v174, v175
	v_add_f32_e32 v196, v176, v177
	v_pk_mul_f32 v[52:53], v[48:49], v[36:37] op_sel_hi:[0,1]
	ds_read_b128 v[16:19], v156 offset:2864
	v_add_f32_dpp v174, v174, v174 row_ror:8 row_mask:0xf bank_mask:0xf bound_ctrl:1
	v_pk_mul_f32 v[54:55], v[48:49], v[38:39] op_sel_hi:[0,1]
	v_pk_fma_f32 v[56:57], v[68:69], v[44:45], v[52:53]
	v_add_f32_dpp v174, v174, v174 row_ror:4 row_mask:0xf bank_mask:0xf bound_ctrl:1
	v_pk_fma_f32 v[58:59], v[70:71], v[46:47], v[54:55]
	s_waitcnt vmcnt(12)
	v_add_f32_dpp v174, v174, v174 row_ror:2 row_mask:0xf bank_mask:0xf bound_ctrl:1
	v_lshlrev_b32_e32 v136, 16, v88
	v_and_b32_e32 v137, 0xffff0000, v88
	v_add_f32_dpp v174, v174, v174 row_ror:1 row_mask:0xf bank_mask:0xf bound_ctrl:1
	v_add_f32_dpp v230, v180, v180 row_mirror row_mask:0xf bank_mask:0xf bound_ctrl:1
	v_add_f32_dpp v230, v188, v188 row_mirror row_mask:0xf bank_mask:0xc bound_ctrl:1
	v_pk_fma_f32 v[68:69], v[174:175], v[32:33], v[56:57] op_sel_hi:[0,1,1] neg_lo:[1,0,0] neg_hi:[1,0,0]
	v_pk_fma_f32 v[70:71], v[174:175], v[34:35], v[58:59] op_sel_hi:[0,1,1] neg_lo:[1,0,0] neg_hi:[1,0,0]
	s_waitcnt lgkmcnt(0)
	ds_read_b128 v[28:31], v156 offset:4224
	ds_read_b128 v[36:39], v156 offset:4256
	ds_read_u16_d16_hi v48, v157 offset:4224
	ds_read_b128 v[44:47], v156 offset:4288
	ds_read_b128 v[32:35], v156 offset:4240
	v_pk_mul_f32 v[172:173], v[68:69], v[4:5]
	v_pk_mul_f32 v[178:179], v[68:69], v[40:41]
	v_pk_fma_f32 v[172:173], v[70:71], v[6:7], v[172:173]
	v_pk_fma_f32 v[178:179], v[70:71], v[42:43], v[178:179]
	v_add_f32_e32 v172, v172, v173
	v_add_f32_e32 v197, v178, v179
	v_pk_mul_f32 v[52:53], v[24:25], v[12:13] op_sel_hi:[0,1]
	ds_read_b128 v[40:43], v156 offset:4272
	v_add_f32_dpp v172, v172, v172 row_ror:8 row_mask:0xf bank_mask:0xf bound_ctrl:1
	v_pk_mul_f32 v[54:55], v[24:25], v[14:15] op_sel_hi:[0,1]
	v_pk_fma_f32 v[56:57], v[68:69], v[20:21], v[52:53]
	v_add_f32_dpp v172, v172, v172 row_ror:4 row_mask:0xf bank_mask:0xf bound_ctrl:1
	v_pk_fma_f32 v[58:59], v[70:71], v[22:23], v[54:55]
	v_lshlrev_b32_e32 v138, 16, v89
	v_add_f32_dpp v172, v172, v172 row_ror:2 row_mask:0xf bank_mask:0xf bound_ctrl:1
	v_and_b32_e32 v139, 0xffff0000, v89
	v_lshlrev_b32_e32 v140, 16, v90
	v_add_f32_dpp v172, v172, v172 row_ror:1 row_mask:0xf bank_mask:0xf bound_ctrl:1
	v_add_f32_dpp v231, v181, v181 row_mirror row_mask:0xf bank_mask:0xf bound_ctrl:1
	v_add_f32_dpp v231, v189, v189 row_mirror row_mask:0xf bank_mask:0xc bound_ctrl:1
	v_pk_fma_f32 v[68:69], v[172:173], v[8:9], v[56:57] op_sel_hi:[0,1,1] neg_lo:[1,0,0] neg_hi:[1,0,0]
	v_pk_fma_f32 v[70:71], v[172:173], v[10:11], v[58:59] op_sel_hi:[0,1,1] neg_lo:[1,0,0] neg_hi:[1,0,0]
	s_waitcnt lgkmcnt(0)
	ds_read_b128 v[4:7], v156 offset:5632
	ds_read_b128 v[12:15], v156 offset:5664
	ds_read_u16_d16_hi v24, v157 offset:5632
	ds_read_b128 v[20:23], v156 offset:5696
	ds_read_b128 v[8:11], v156 offset:5648
	v_pk_mul_f32 v[174:175], v[68:69], v[28:29]
	v_pk_mul_f32 v[176:177], v[68:69], v[16:17]
	v_pk_fma_f32 v[174:175], v[70:71], v[30:31], v[174:175]
	v_pk_fma_f32 v[176:177], v[70:71], v[18:19], v[176:177]
	v_add_f32_e32 v174, v174, v175
	v_add_f32_e32 v198, v176, v177
	v_pk_mul_f32 v[52:53], v[48:49], v[36:37] op_sel_hi:[0,1]
	ds_read_b128 v[16:19], v156 offset:5680
	v_add_f32_dpp v174, v174, v174 row_ror:8 row_mask:0xf bank_mask:0xf bound_ctrl:1
	v_pk_mul_f32 v[54:55], v[48:49], v[38:39] op_sel_hi:[0,1]
	v_pk_fma_f32 v[56:57], v[68:69], v[44:45], v[52:53]
	v_add_f32_dpp v174, v174, v174 row_ror:4 row_mask:0xf bank_mask:0xf bound_ctrl:1
	v_pk_fma_f32 v[58:59], v[70:71], v[46:47], v[54:55]
	v_and_b32_e32 v141, 0xffff0000, v90
	v_add_f32_dpp v174, v174, v174 row_ror:2 row_mask:0xf bank_mask:0xf bound_ctrl:1
	v_lshlrev_b32_e32 v142, 16, v91
	v_and_b32_e32 v143, 0xffff0000, v91
	v_add_f32_dpp v174, v174, v174 row_ror:1 row_mask:0xf bank_mask:0xf bound_ctrl:1
	v_add_f32_dpp v232, v182, v182 row_mirror row_mask:0xf bank_mask:0xf bound_ctrl:1
	v_add_f32_dpp v232, v190, v190 row_mirror row_mask:0xf bank_mask:0xc bound_ctrl:1
	v_pk_fma_f32 v[68:69], v[174:175], v[32:33], v[56:57] op_sel_hi:[0,1,1] neg_lo:[1,0,0] neg_hi:[1,0,0]
	v_pk_fma_f32 v[70:71], v[174:175], v[34:35], v[58:59] op_sel_hi:[0,1,1] neg_lo:[1,0,0] neg_hi:[1,0,0]
	s_waitcnt lgkmcnt(0)
	ds_read_b128 v[28:31], v156 offset:7040
	ds_read_b128 v[36:39], v156 offset:7072
	ds_read_u16_d16_hi v48, v157 offset:7040
	ds_read_b128 v[44:47], v156 offset:7104
	ds_read_b128 v[32:35], v156 offset:7056
	v_pk_mul_f32 v[172:173], v[68:69], v[4:5]
	v_pk_mul_f32 v[178:179], v[68:69], v[40:41]
	v_pk_fma_f32 v[172:173], v[70:71], v[6:7], v[172:173]
	v_pk_fma_f32 v[178:179], v[70:71], v[42:43], v[178:179]
	v_add_f32_e32 v172, v172, v173
	v_add_f32_e32 v199, v178, v179
	v_pk_mul_f32 v[52:53], v[24:25], v[12:13] op_sel_hi:[0,1]
	ds_read_b128 v[40:43], v156 offset:7088
	v_add_f32_dpp v172, v172, v172 row_ror:8 row_mask:0xf bank_mask:0xf bound_ctrl:1
	v_pk_mul_f32 v[54:55], v[24:25], v[14:15] op_sel_hi:[0,1]
	v_pk_fma_f32 v[56:57], v[68:69], v[20:21], v[52:53]
	v_add_f32_dpp v172, v172, v172 row_ror:4 row_mask:0xf bank_mask:0xf bound_ctrl:1
	v_pk_fma_f32 v[58:59], v[70:71], v[22:23], v[54:55]
	ds_write_b128 v155, v[136:139] offset:0
	v_add_f32_dpp v172, v172, v172 row_ror:2 row_mask:0xf bank_mask:0xf bound_ctrl:1
	ds_write_b128 v155, v[140:143] offset:80
	v_lshlrev_b32_e32 v136, 16, v92
	v_add_f32_dpp v172, v172, v172 row_ror:1 row_mask:0xf bank_mask:0xf bound_ctrl:1
	v_add_f32_dpp v233, v183, v183 row_mirror row_mask:0xf bank_mask:0xf bound_ctrl:1
	v_add_f32_dpp v233, v191, v191 row_mirror row_mask:0xf bank_mask:0xc bound_ctrl:1
	v_pk_fma_f32 v[68:69], v[172:173], v[8:9], v[56:57] op_sel_hi:[0,1,1] neg_lo:[1,0,0] neg_hi:[1,0,0]
	v_pk_fma_f32 v[70:71], v[172:173], v[10:11], v[58:59] op_sel_hi:[0,1,1] neg_lo:[1,0,0] neg_hi:[1,0,0]
	v_add_f32_dpp v234, v184, v184 row_mirror row_mask:0xf bank_mask:0xf bound_ctrl:1
	s_waitcnt lgkmcnt(2)
	ds_read_b128 v[4:7], v156 offset:8448
	ds_read_b128 v[12:15], v156 offset:8480
	ds_read_u16_d16_hi v24, v157 offset:8448
	ds_read_b128 v[20:23], v156 offset:8512
	ds_read_b128 v[8:11], v156 offset:8464
	v_pk_mul_f32 v[174:175], v[68:69], v[28:29]
	v_pk_mul_f32 v[176:177], v[68:69], v[16:17]
	v_pk_fma_f32 v[174:175], v[70:71], v[30:31], v[174:175]
	v_pk_fma_f32 v[176:177], v[70:71], v[18:19], v[176:177]
	v_add_f32_e32 v174, v174, v175
	v_add_f32_e32 v200, v176, v177
	v_pk_mul_f32 v[52:53], v[48:49], v[36:37] op_sel_hi:[0,1]
	ds_read_b128 v[16:19], v156 offset:8496
	v_add_f32_dpp v174, v174, v174 row_ror:8 row_mask:0xf bank_mask:0xf bound_ctrl:1
	v_pk_mul_f32 v[54:55], v[48:49], v[38:39] op_sel_hi:[0,1]
	v_pk_fma_f32 v[56:57], v[68:69], v[44:45], v[52:53]
	v_add_f32_dpp v174, v174, v174 row_ror:4 row_mask:0xf bank_mask:0xf bound_ctrl:1
	v_pk_fma_f32 v[58:59], v[70:71], v[46:47], v[54:55]
	v_and_b32_e32 v137, 0xffff0000, v92
	v_add_f32_dpp v174, v174, v174 row_ror:2 row_mask:0xf bank_mask:0xf bound_ctrl:1
	v_lshlrev_b32_e32 v138, 16, v93
	v_and_b32_e32 v139, 0xffff0000, v93
	v_add_f32_dpp v174, v174, v174 row_ror:1 row_mask:0xf bank_mask:0xf bound_ctrl:1
	v_add_f32_dpp v234, v192, v192 row_mirror row_mask:0xf bank_mask:0xc bound_ctrl:1
	v_add_f32_dpp v235, v185, v185 row_mirror row_mask:0xf bank_mask:0xf bound_ctrl:1
	v_pk_fma_f32 v[68:69], v[174:175], v[32:33], v[56:57] op_sel_hi:[0,1,1] neg_lo:[1,0,0] neg_hi:[1,0,0]
	v_pk_fma_f32 v[70:71], v[174:175], v[34:35], v[58:59] op_sel_hi:[0,1,1] neg_lo:[1,0,0] neg_hi:[1,0,0]
	s_waitcnt lgkmcnt(0)
	ds_read_b128 v[28:31], v156 offset:9856
	ds_read_b128 v[36:39], v156 offset:9888
	ds_read_u16_d16_hi v48, v157 offset:9856
	ds_read_b128 v[44:47], v156 offset:9920
	ds_read_b128 v[32:35], v156 offset:9872
	v_pk_mul_f32 v[172:173], v[68:69], v[4:5]
	v_pk_mul_f32 v[178:179], v[68:69], v[40:41]
	v_pk_fma_f32 v[172:173], v[70:71], v[6:7], v[172:173]
	v_pk_fma_f32 v[178:179], v[70:71], v[42:43], v[178:179]
	v_add_f32_e32 v172, v172, v173
	v_add_f32_e32 v201, v178, v179
	v_pk_mul_f32 v[52:53], v[24:25], v[12:13] op_sel_hi:[0,1]
	ds_read_b128 v[40:43], v156 offset:9904
	v_add_f32_dpp v172, v172, v172 row_ror:8 row_mask:0xf bank_mask:0xf bound_ctrl:1
	v_pk_mul_f32 v[54:55], v[24:25], v[14:15] op_sel_hi:[0,1]
	v_pk_fma_f32 v[56:57], v[68:69], v[20:21], v[52:53]
	v_add_f32_dpp v172, v172, v172 row_ror:4 row_mask:0xf bank_mask:0xf bound_ctrl:1
	v_pk_fma_f32 v[58:59], v[70:71], v[22:23], v[54:55]
	v_lshlrev_b32_e32 v140, 16, v94
	v_add_f32_dpp v172, v172, v172 row_ror:2 row_mask:0xf bank_mask:0xf bound_ctrl:1
	v_and_b32_e32 v141, 0xffff0000, v94
	v_lshlrev_b32_e32 v142, 16, v95
	v_add_f32_dpp v172, v172, v172 row_ror:1 row_mask:0xf bank_mask:0xf bound_ctrl:1
	v_add_f32_dpp v235, v193, v193 row_mirror row_mask:0xf bank_mask:0xc bound_ctrl:1
	v_add_f32_dpp v236, v186, v186 row_mirror row_mask:0xf bank_mask:0xf bound_ctrl:1
	v_pk_fma_f32 v[68:69], v[172:173], v[8:9], v[56:57] op_sel_hi:[0,1,1] neg_lo:[1,0,0] neg_hi:[1,0,0]
	v_pk_fma_f32 v[70:71], v[172:173], v[10:11], v[58:59] op_sel_hi:[0,1,1] neg_lo:[1,0,0] neg_hi:[1,0,0]
	s_waitcnt lgkmcnt(0)
	ds_read_b128 v[4:7], v156 offset:11264
	ds_read_b128 v[12:15], v156 offset:11296
	ds_read_u16_d16_hi v24, v157 offset:11264
	ds_read_b128 v[20:23], v156 offset:11328
	ds_read_b128 v[8:11], v156 offset:11280
	v_pk_mul_f32 v[174:175], v[68:69], v[28:29]
	v_pk_mul_f32 v[176:177], v[68:69], v[16:17]
	v_pk_fma_f32 v[174:175], v[70:71], v[30:31], v[174:175]
	v_pk_fma_f32 v[176:177], v[70:71], v[18:19], v[176:177]
	v_add_f32_e32 v174, v174, v175
	v_add_f32_e32 v210, v176, v177
	v_pk_mul_f32 v[52:53], v[48:49], v[36:37] op_sel_hi:[0,1]
	ds_read_b128 v[16:19], v156 offset:11312
	v_add_f32_dpp v174, v174, v174 row_ror:8 row_mask:0xf bank_mask:0xf bound_ctrl:1
	v_pk_mul_f32 v[54:55], v[48:49], v[38:39] op_sel_hi:[0,1]
	v_pk_fma_f32 v[56:57], v[68:69], v[44:45], v[52:53]
	v_add_f32_dpp v174, v174, v174 row_ror:4 row_mask:0xf bank_mask:0xf bound_ctrl:1
	v_pk_fma_f32 v[58:59], v[70:71], v[46:47], v[54:55]
	v_and_b32_e32 v143, 0xffff0000, v95
	v_add_f32_dpp v174, v174, v174 row_ror:2 row_mask:0xf bank_mask:0xf bound_ctrl:1
	ds_write_b128 v155, v[136:139] offset:11264
	ds_write_b128 v155, v[140:143] offset:11344
	v_add_f32_dpp v174, v174, v174 row_ror:1 row_mask:0xf bank_mask:0xf bound_ctrl:1
	v_add_f32_dpp v236, v194, v194 row_mirror row_mask:0xf bank_mask:0xc bound_ctrl:1
	v_add_f32_dpp v237, v187, v187 row_mirror row_mask:0xf bank_mask:0xf bound_ctrl:1
	v_pk_fma_f32 v[68:69], v[174:175], v[32:33], v[56:57] op_sel_hi:[0,1,1] neg_lo:[1,0,0] neg_hi:[1,0,0]
	v_pk_fma_f32 v[70:71], v[174:175], v[34:35], v[58:59] op_sel_hi:[0,1,1] neg_lo:[1,0,0] neg_hi:[1,0,0]
	s_waitcnt lgkmcnt(2)
	ds_read_b128 v[28:31], v156 offset:12672
	ds_read_b128 v[36:39], v156 offset:12704
	ds_read_u16_d16_hi v48, v157 offset:12672
	ds_read_b128 v[44:47], v156 offset:12736
	ds_read_b128 v[32:35], v156 offset:12688
	v_pk_mul_f32 v[172:173], v[68:69], v[4:5]
	v_pk_mul_f32 v[178:179], v[68:69], v[40:41]
	v_pk_fma_f32 v[172:173], v[70:71], v[6:7], v[172:173]
	v_pk_fma_f32 v[178:179], v[70:71], v[42:43], v[178:179]
	v_add_f32_e32 v172, v172, v173
	v_add_f32_e32 v211, v178, v179
	v_pk_mul_f32 v[52:53], v[24:25], v[12:13] op_sel_hi:[0,1]
	ds_read_b128 v[40:43], v156 offset:12720
	v_add_f32_dpp v172, v172, v172 row_ror:8 row_mask:0xf bank_mask:0xf bound_ctrl:1
	v_pk_mul_f32 v[54:55], v[24:25], v[14:15] op_sel_hi:[0,1]
	v_pk_fma_f32 v[56:57], v[68:69], v[20:21], v[52:53]
	v_add_f32_dpp v172, v172, v172 row_ror:4 row_mask:0xf bank_mask:0xf bound_ctrl:1
	v_pk_fma_f32 v[58:59], v[70:71], v[22:23], v[54:55]
	ds_write_b128 v165, v[96:99]
	v_add_f32_dpp v172, v172, v172 row_ror:2 row_mask:0xf bank_mask:0xf bound_ctrl:1
	ds_write_b128 v166, v[100:103]
	global_load_dwordx4 v[88:91], v[144:145], off
	v_add_f32_dpp v172, v172, v172 row_ror:1 row_mask:0xf bank_mask:0xf bound_ctrl:1
	v_add_f32_dpp v237, v195, v195 row_mirror row_mask:0xf bank_mask:0xc bound_ctrl:1
	v_add_f32_dpp v238, v230, v230 row_half_mirror row_mask:0xf bank_mask:0xf bound_ctrl:1
	v_pk_fma_f32 v[68:69], v[172:173], v[8:9], v[56:57] op_sel_hi:[0,1,1] neg_lo:[1,0,0] neg_hi:[1,0,0]
	v_pk_fma_f32 v[70:71], v[172:173], v[10:11], v[58:59] op_sel_hi:[0,1,1] neg_lo:[1,0,0] neg_hi:[1,0,0]
	v_add_f32_dpp v238, v234, v234 row_half_mirror row_mask:0xf bank_mask:0xa bound_ctrl:1
	s_waitcnt lgkmcnt(2)
	ds_read_b128 v[4:7], v156 offset:14080
	ds_read_b128 v[12:15], v156 offset:14112
	ds_read_u16_d16_hi v24, v157 offset:14080
	ds_read_b128 v[20:23], v156 offset:14144
	ds_read_b128 v[8:11], v156 offset:14096
	v_pk_mul_f32 v[174:175], v[68:69], v[28:29]
	v_pk_mul_f32 v[176:177], v[68:69], v[16:17]
	v_pk_fma_f32 v[174:175], v[70:71], v[30:31], v[174:175]
	v_pk_fma_f32 v[176:177], v[70:71], v[18:19], v[176:177]
	v_add_f32_e32 v174, v174, v175
	v_add_f32_e32 v212, v176, v177
	v_pk_mul_f32 v[52:53], v[48:49], v[36:37] op_sel_hi:[0,1]
	ds_read_b128 v[16:19], v156 offset:14128
	v_add_f32_dpp v174, v174, v174 row_ror:8 row_mask:0xf bank_mask:0xf bound_ctrl:1
	v_pk_mul_f32 v[54:55], v[48:49], v[38:39] op_sel_hi:[0,1]
	v_pk_fma_f32 v[56:57], v[68:69], v[44:45], v[52:53]
	v_add_f32_dpp v174, v174, v174 row_ror:4 row_mask:0xf bank_mask:0xf bound_ctrl:1
	v_pk_fma_f32 v[58:59], v[70:71], v[46:47], v[54:55]
	global_load_dwordx4 v[92:95], v[146:147], off
	v_add_f32_dpp v174, v174, v174 row_ror:2 row_mask:0xf bank_mask:0xf bound_ctrl:1
	global_load_dwordx4 v[96:99], v[148:149], off
	global_load_dwordx4 v[100:103], v[150:151], off
	v_add_f32_dpp v174, v174, v174 row_ror:1 row_mask:0xf bank_mask:0xf bound_ctrl:1
	v_add_f32_dpp v239, v231, v231 row_half_mirror row_mask:0xf bank_mask:0xf bound_ctrl:1
	v_add_f32_dpp v239, v235, v235 row_half_mirror row_mask:0xf bank_mask:0xa bound_ctrl:1
	v_pk_fma_f32 v[68:69], v[174:175], v[32:33], v[56:57] op_sel_hi:[0,1,1] neg_lo:[1,0,0] neg_hi:[1,0,0]
	v_pk_fma_f32 v[70:71], v[174:175], v[34:35], v[58:59] op_sel_hi:[0,1,1] neg_lo:[1,0,0] neg_hi:[1,0,0]
	s_waitcnt lgkmcnt(0)
	ds_read_b128 v[28:31], v156 offset:15488
	ds_read_b128 v[36:39], v156 offset:15520
	ds_read_u16_d16_hi v48, v157 offset:15488
	ds_read_b128 v[44:47], v156 offset:15552
	ds_read_b128 v[32:35], v156 offset:15504
	v_pk_mul_f32 v[172:173], v[68:69], v[4:5]
	v_pk_mul_f32 v[178:179], v[68:69], v[40:41]
	v_pk_fma_f32 v[172:173], v[70:71], v[6:7], v[172:173]
	v_pk_fma_f32 v[178:179], v[70:71], v[42:43], v[178:179]
	v_add_f32_e32 v172, v172, v173
	v_add_f32_e32 v213, v178, v179
	v_pk_mul_f32 v[52:53], v[24:25], v[12:13] op_sel_hi:[0,1]
	ds_read_b128 v[40:43], v156 offset:15536
	v_add_f32_dpp v172, v172, v172 row_ror:8 row_mask:0xf bank_mask:0xf bound_ctrl:1
	v_pk_mul_f32 v[54:55], v[24:25], v[14:15] op_sel_hi:[0,1]
	v_pk_fma_f32 v[56:57], v[68:69], v[20:21], v[52:53]
	v_add_f32_dpp v172, v172, v172 row_ror:4 row_mask:0xf bank_mask:0xf bound_ctrl:1
	v_pk_fma_f32 v[58:59], v[70:71], v[22:23], v[54:55]
	v_lshl_add_u64 v[144:145], v[144:145], 0, v[152:153]
	v_add_f32_dpp v172, v172, v172 row_ror:2 row_mask:0xf bank_mask:0xf bound_ctrl:1
	v_lshl_add_u64 v[146:147], v[146:147], 0, v[152:153]
	v_lshl_add_u64 v[148:149], v[148:149], 0, v[62:63]
	v_add_f32_dpp v172, v172, v172 row_ror:1 row_mask:0xf bank_mask:0xf bound_ctrl:1
	v_add_f32_dpp v240, v232, v232 row_half_mirror row_mask:0xf bank_mask:0xf bound_ctrl:1
	v_add_f32_dpp v240, v236, v236 row_half_mirror row_mask:0xf bank_mask:0xa bound_ctrl:1
	v_pk_fma_f32 v[68:69], v[172:173], v[8:9], v[56:57] op_sel_hi:[0,1,1] neg_lo:[1,0,0] neg_hi:[1,0,0]
	v_pk_fma_f32 v[70:71], v[172:173], v[10:11], v[58:59] op_sel_hi:[0,1,1] neg_lo:[1,0,0] neg_hi:[1,0,0]
	s_waitcnt lgkmcnt(0)
	ds_read_b128 v[4:7], v156 offset:16896
	ds_read_b128 v[12:15], v156 offset:16928
	ds_read_u16_d16_hi v24, v157 offset:16896
	ds_read_b128 v[20:23], v156 offset:16960
	ds_read_b128 v[8:11], v156 offset:16912
	v_pk_mul_f32 v[174:175], v[68:69], v[28:29]
	v_pk_mul_f32 v[176:177], v[68:69], v[16:17]
	v_pk_fma_f32 v[174:175], v[70:71], v[30:31], v[174:175]
	v_pk_fma_f32 v[176:177], v[70:71], v[18:19], v[176:177]
	v_add_f32_e32 v174, v174, v175
	v_add_f32_e32 v220, v176, v177
	v_pk_mul_f32 v[52:53], v[48:49], v[36:37] op_sel_hi:[0,1]
	ds_read_b128 v[16:19], v156 offset:16944
	v_add_f32_dpp v174, v174, v174 row_ror:8 row_mask:0xf bank_mask:0xf bound_ctrl:1
	v_pk_mul_f32 v[54:55], v[48:49], v[38:39] op_sel_hi:[0,1]
	v_pk_fma_f32 v[56:57], v[68:69], v[44:45], v[52:53]
	v_add_f32_dpp v174, v174, v174 row_ror:4 row_mask:0xf bank_mask:0xf bound_ctrl:1
	v_pk_fma_f32 v[58:59], v[70:71], v[46:47], v[54:55]
	v_lshl_add_u64 v[150:151], v[150:151], 0, v[64:65]
	v_add_f32_dpp v174, v174, v174 row_ror:2 row_mask:0xf bank_mask:0xf bound_ctrl:1
	v_add_u32_e32 v158, s43, v162
	v_add_u32_e32 v159, s43, v163
	v_add_f32_dpp v174, v174, v174 row_ror:1 row_mask:0xf bank_mask:0xf bound_ctrl:1
	v_add_f32_dpp v241, v233, v233 row_half_mirror row_mask:0xf bank_mask:0xf bound_ctrl:1
	v_add_f32_dpp v241, v237, v237 row_half_mirror row_mask:0xf bank_mask:0xa bound_ctrl:1
	v_pk_fma_f32 v[68:69], v[174:175], v[32:33], v[56:57] op_sel_hi:[0,1,1] neg_lo:[1,0,0] neg_hi:[1,0,0]
	v_pk_fma_f32 v[70:71], v[174:175], v[34:35], v[58:59] op_sel_hi:[0,1,1] neg_lo:[1,0,0] neg_hi:[1,0,0]
	s_waitcnt lgkmcnt(0)
	ds_read_b128 v[28:31], v156 offset:18304
	ds_read_b128 v[36:39], v156 offset:18336
	ds_read_u16_d16_hi v48, v157 offset:18304
	ds_read_b128 v[44:47], v156 offset:18368
	ds_read_b128 v[32:35], v156 offset:18320
	v_pk_mul_f32 v[172:173], v[68:69], v[4:5]
	v_pk_mul_f32 v[178:179], v[68:69], v[40:41]
	v_pk_fma_f32 v[172:173], v[70:71], v[6:7], v[172:173]
	v_pk_fma_f32 v[178:179], v[70:71], v[42:43], v[178:179]
	v_add_f32_e32 v172, v172, v173
	v_add_f32_e32 v221, v178, v179
	v_pk_mul_f32 v[52:53], v[24:25], v[12:13] op_sel_hi:[0,1]
	ds_read_b128 v[40:43], v156 offset:18352
	v_add_f32_dpp v172, v172, v172 row_ror:8 row_mask:0xf bank_mask:0xf bound_ctrl:1
	v_pk_mul_f32 v[54:55], v[24:25], v[14:15] op_sel_hi:[0,1]
	v_pk_fma_f32 v[56:57], v[68:69], v[20:21], v[52:53]
	v_add_f32_dpp v172, v172, v172 row_ror:4 row_mask:0xf bank_mask:0xf bound_ctrl:1
	v_pk_fma_f32 v[58:59], v[70:71], v[22:23], v[54:55]
	v_add_f32_dpp v242, v238, v238 quad_perm:[3,2,1,0] row_mask:0xf bank_mask:0xf bound_ctrl:1
	v_add_f32_dpp v172, v172, v172 row_ror:2 row_mask:0xf bank_mask:0xf bound_ctrl:1
	v_add_f32_dpp v243, v240, v240 quad_perm:[3,2,1,0] row_mask:0xf bank_mask:0xf bound_ctrl:1
	v_cndmask_b32_e64 v244, v242, v243, s[4:5]
	v_add_f32_dpp v172, v172, v172 row_ror:1 row_mask:0xf bank_mask:0xf bound_ctrl:1
	v_pk_fma_f32 v[68:69], v[172:173], v[8:9], v[56:57] op_sel_hi:[0,1,1] neg_lo:[1,0,0] neg_hi:[1,0,0]
	v_pk_fma_f32 v[70:71], v[172:173], v[10:11], v[58:59] op_sel_hi:[0,1,1] neg_lo:[1,0,0] neg_hi:[1,0,0]
	s_waitcnt lgkmcnt(0)
	ds_read_b128 v[4:7], v156 offset:19712
	ds_read_b128 v[12:15], v156 offset:19744
	ds_read_u16_d16_hi v24, v157 offset:19712
	ds_read_b128 v[20:23], v156 offset:19776
	ds_read_b128 v[8:11], v156 offset:19728
	v_pk_mul_f32 v[174:175], v[68:69], v[28:29]
	v_pk_mul_f32 v[176:177], v[68:69], v[16:17]
	v_pk_fma_f32 v[174:175], v[70:71], v[30:31], v[174:175]
	v_pk_fma_f32 v[176:177], v[70:71], v[18:19], v[176:177]
	v_add_f32_e32 v174, v174, v175
	v_add_f32_e32 v222, v176, v177
	v_pk_mul_f32 v[52:53], v[48:49], v[36:37] op_sel_hi:[0,1]
	ds_read_b128 v[16:19], v156 offset:19760
	v_add_f32_dpp v174, v174, v174 row_ror:8 row_mask:0xf bank_mask:0xf bound_ctrl:1
	v_pk_mul_f32 v[54:55], v[48:49], v[38:39] op_sel_hi:[0,1]
	v_pk_fma_f32 v[56:57], v[68:69], v[44:45], v[52:53]
	v_add_f32_dpp v174, v174, v174 row_ror:4 row_mask:0xf bank_mask:0xf bound_ctrl:1
	v_pk_fma_f32 v[58:59], v[70:71], v[46:47], v[54:55]
	v_add_f32_dpp v242, v239, v239 quad_perm:[3,2,1,0] row_mask:0xf bank_mask:0xf bound_ctrl:1
	v_add_f32_dpp v174, v174, v174 row_ror:2 row_mask:0xf bank_mask:0xf bound_ctrl:1
	v_add_f32_dpp v243, v241, v241 quad_perm:[3,2,1,0] row_mask:0xf bank_mask:0xf bound_ctrl:1
	s_nop 0
	v_add_f32_dpp v174, v174, v174 row_ror:1 row_mask:0xf bank_mask:0xf bound_ctrl:1
	v_pk_fma_f32 v[68:69], v[174:175], v[32:33], v[56:57] op_sel_hi:[0,1,1] neg_lo:[1,0,0] neg_hi:[1,0,0]
	v_pk_fma_f32 v[70:71], v[174:175], v[34:35], v[58:59] op_sel_hi:[0,1,1] neg_lo:[1,0,0] neg_hi:[1,0,0]
	s_waitcnt lgkmcnt(0)
	ds_read_b128 v[28:31], v156 offset:21120
	ds_read_b128 v[36:39], v156 offset:21152
	ds_read_u16_d16_hi v48, v157 offset:21120
	ds_read_b128 v[44:47], v156 offset:21184
	ds_read_b128 v[32:35], v156 offset:21136
	v_pk_mul_f32 v[172:173], v[68:69], v[4:5]
	v_pk_mul_f32 v[178:179], v[68:69], v[40:41]
	v_pk_fma_f32 v[172:173], v[70:71], v[6:7], v[172:173]
	v_pk_fma_f32 v[178:179], v[70:71], v[42:43], v[178:179]
	v_add_f32_e32 v172, v172, v173
	v_add_f32_e32 v223, v178, v179
	v_pk_mul_f32 v[52:53], v[24:25], v[12:13] op_sel_hi:[0,1]
	ds_read_b128 v[40:43], v156 offset:21168
	v_add_f32_dpp v172, v172, v172 row_ror:8 row_mask:0xf bank_mask:0xf bound_ctrl:1
	v_pk_mul_f32 v[54:55], v[24:25], v[14:15] op_sel_hi:[0,1]
	v_pk_fma_f32 v[56:57], v[68:69], v[20:21], v[52:53]
	v_add_f32_dpp v172, v172, v172 row_ror:4 row_mask:0xf bank_mask:0xf bound_ctrl:1
	v_pk_fma_f32 v[58:59], v[70:71], v[22:23], v[54:55]
	v_cndmask_b32_e64 v245, v242, v243, s[4:5]
	v_add_f32_dpp v172, v172, v172 row_ror:2 row_mask:0xf bank_mask:0xf bound_ctrl:1
	v_add_f32_dpp v242, v244, v244 quad_perm:[1,0,3,2] row_mask:0xf bank_mask:0xf bound_ctrl:1
	s_nop 0
	v_add_f32_dpp v172, v172, v172 row_ror:1 row_mask:0xf bank_mask:0xf bound_ctrl:1
	v_pk_fma_f32 v[68:69], v[172:173], v[8:9], v[56:57] op_sel_hi:[0,1,1] neg_lo:[1,0,0] neg_hi:[1,0,0]
	v_pk_fma_f32 v[70:71], v[172:173], v[10:11], v[58:59] op_sel_hi:[0,1,1] neg_lo:[1,0,0] neg_hi:[1,0,0]
	s_waitcnt lgkmcnt(0)
; DEVI void rw_chain_task(const Params& p, int l, int seq, int head, int quarter, char* smem) {
;     ...
;   __syncthreads();
;     ...
;   float* so = seq < 2 ? p.out + O_PRWS + ((((size_t)l * 2 + seq) * 12 + head) * 64 + i) * 64 + jl * 4
;                       : p.out + O_SRWS + ((((size_t)l * 8 + (seq - 2)) * 12 + head) * 64 + i) * 64 + jl * 4;
;   *(float4*)so = make_float4(S[0], S[1], S[2], S[3]);
	ds_read_b128 v[4:7], v158 offset:0
	ds_read_b128 v[12:15], v158 offset:32
	ds_read_u16_d16_hi v24, v159 offset:0
	ds_read_b128 v[20:23], v158 offset:64
	ds_read_b128 v[8:11], v158 offset:16
	v_pk_mul_f32 v[174:175], v[68:69], v[28:29]
	v_pk_mul_f32 v[176:177], v[68:69], v[16:17]
	v_pk_fma_f32 v[174:175], v[70:71], v[30:31], v[174:175]
	v_pk_fma_f32 v[176:177], v[70:71], v[18:19], v[176:177]
	v_add_f32_e32 v174, v174, v175
	v_add_f32_e32 v224, v176, v177
	v_pk_mul_f32 v[52:53], v[48:49], v[36:37] op_sel_hi:[0,1]
	ds_read_b128 v[16:19], v158 offset:48
	v_add_f32_dpp v174, v174, v174 row_ror:8 row_mask:0xf bank_mask:0xf bound_ctrl:1
	v_pk_mul_f32 v[54:55], v[48:49], v[38:39] op_sel_hi:[0,1]
	v_pk_fma_f32 v[56:57], v[68:69], v[44:45], v[52:53]
	v_add_f32_dpp v174, v174, v174 row_ror:4 row_mask:0xf bank_mask:0xf bound_ctrl:1
	v_pk_fma_f32 v[58:59], v[70:71], v[46:47], v[54:55]
	v_add_f32_dpp v243, v245, v245 quad_perm:[1,0,3,2] row_mask:0xf bank_mask:0xf bound_ctrl:1
	v_add_f32_dpp v174, v174, v174 row_ror:2 row_mask:0xf bank_mask:0xf bound_ctrl:1
	v_cndmask_b32_e64 v246, v242, v243, s[6:7]
	v_bfe_u32 v61, v246, 16, 1
	v_add3_u32 v61, v246, v61, s33
	global_store_short_d16_hi v[160:161], v61, off
	v_lshl_add_u64 v[160:161], v[160:161], 0, s[46:47]
	v_add_f32_dpp v174, v174, v174 row_ror:1 row_mask:0xf bank_mask:0xf bound_ctrl:1
	v_pk_fma_f32 v[68:69], v[174:175], v[32:33], v[56:57] op_sel_hi:[0,1,1] neg_lo:[1,0,0] neg_hi:[1,0,0]
	v_pk_fma_f32 v[70:71], v[174:175], v[34:35], v[58:59] op_sel_hi:[0,1,1] neg_lo:[1,0,0] neg_hi:[1,0,0]
	s_add_u32 s41, s41, 4
	s_cmpk_lt_u32 s41, 0x400
	s_cbranch_scc1 .Lrwc_loop
	s_waitcnt lgkmcnt(0)
	v_pk_mul_f32 v[178:179], v[68:69], v[40:41]
	v_pk_fma_f32 v[178:179], v[70:71], v[42:43], v[178:179]
	v_add_f32_e32 v225, v178, v179
	v_add_f32_dpp v230, v196, v196 row_mirror row_mask:0xf bank_mask:0xf bound_ctrl:1
	v_add_f32_dpp v230, v212, v212 row_mirror row_mask:0xf bank_mask:0xc bound_ctrl:1
	v_add_f32_dpp v231, v197, v197 row_mirror row_mask:0xf bank_mask:0xf bound_ctrl:1
	v_add_f32_dpp v231, v213, v213 row_mirror row_mask:0xf bank_mask:0xc bound_ctrl:1
	v_add_f32_dpp v232, v198, v198 row_mirror row_mask:0xf bank_mask:0xf bound_ctrl:1
	v_add_f32_dpp v232, v220, v220 row_mirror row_mask:0xf bank_mask:0xc bound_ctrl:1
	v_add_f32_dpp v233, v199, v199 row_mirror row_mask:0xf bank_mask:0xf bound_ctrl:1
	v_add_f32_dpp v233, v221, v221 row_mirror row_mask:0xf bank_mask:0xc bound_ctrl:1
	v_add_f32_dpp v234, v200, v200 row_mirror row_mask:0xf bank_mask:0xf bound_ctrl:1
	v_add_f32_dpp v234, v222, v222 row_mirror row_mask:0xf bank_mask:0xc bound_ctrl:1
	v_add_f32_dpp v235, v201, v201 row_mirror row_mask:0xf bank_mask:0xf bound_ctrl:1
	v_add_f32_dpp v235, v223, v223 row_mirror row_mask:0xf bank_mask:0xc bound_ctrl:1
	v_add_f32_dpp v236, v210, v210 row_mirror row_mask:0xf bank_mask:0xf bound_ctrl:1
	v_add_f32_dpp v236, v224, v224 row_mirror row_mask:0xf bank_mask:0xc bound_ctrl:1
	v_add_f32_dpp v237, v211, v211 row_mirror row_mask:0xf bank_mask:0xf bound_ctrl:1
	v_add_f32_dpp v237, v225, v225 row_mirror row_mask:0xf bank_mask:0xc bound_ctrl:1
	v_add_f32_dpp v238, v230, v230 row_half_mirror row_mask:0xf bank_mask:0xf bound_ctrl:1
	v_add_f32_dpp v238, v234, v234 row_half_mirror row_mask:0xf bank_mask:0xa bound_ctrl:1
	v_add_f32_dpp v239, v231, v231 row_half_mirror row_mask:0xf bank_mask:0xf bound_ctrl:1
	v_add_f32_dpp v239, v235, v235 row_half_mirror row_mask:0xf bank_mask:0xa bound_ctrl:1
	v_add_f32_dpp v240, v232, v232 row_half_mirror row_mask:0xf bank_mask:0xf bound_ctrl:1
	v_add_f32_dpp v240, v236, v236 row_half_mirror row_mask:0xf bank_mask:0xa bound_ctrl:1
	v_add_f32_dpp v241, v233, v233 row_half_mirror row_mask:0xf bank_mask:0xf bound_ctrl:1
	v_add_f32_dpp v241, v237, v237 row_half_mirror row_mask:0xf bank_mask:0xa bound_ctrl:1
	v_add_f32_dpp v242, v238, v238 quad_perm:[3,2,1,0] row_mask:0xf bank_mask:0xf bound_ctrl:1
	v_add_f32_dpp v243, v240, v240 quad_perm:[3,2,1,0] row_mask:0xf bank_mask:0xf bound_ctrl:1
	v_cndmask_b32_e64 v244, v242, v243, s[4:5]
	v_add_f32_dpp v242, v239, v239 quad_perm:[3,2,1,0] row_mask:0xf bank_mask:0xf bound_ctrl:1
	v_add_f32_dpp v243, v241, v241 quad_perm:[3,2,1,0] row_mask:0xf bank_mask:0xf bound_ctrl:1
	v_cndmask_b32_e64 v245, v242, v243, s[4:5]
	v_add_f32_dpp v242, v244, v244 quad_perm:[1,0,3,2] row_mask:0xf bank_mask:0xf bound_ctrl:1
	s_nop 0
	v_add_f32_dpp v243, v245, v245 quad_perm:[1,0,3,2] row_mask:0xf bank_mask:0xf bound_ctrl:1
	v_cndmask_b32_e64 v246, v242, v243, s[6:7]
	v_bfe_u32 v61, v246, 16, 1
	v_add3_u32 v61, v246, v61, s33
	global_store_short_d16_hi v[160:161], v61, off
	s_waitcnt vmcnt(0)
	v_cmp_eq_u32_e64 s[4:5], 0, v3
	v_cmp_eq_u32_e64 s[6:7], 1, v3
	v_cmp_eq_u32_e64 s[8:9], 2, v3
	v_cmp_eq_u32_e64 s[10:11], 3, v3
	v_cmp_eq_u32_e64 s[12:13], 4, v3
	v_cmp_eq_u32_e64 s[14:15], 5, v3
	v_cmp_eq_u32_e64 s[16:17], 6, v3
	v_cmp_eq_u32_e64 s[18:19], 7, v3
	v_cmp_eq_u32_e64 s[20:21], 8, v3
	v_cmp_eq_u32_e64 s[22:23], 9, v3
	v_cmp_eq_u32_e64 s[24:25], 10, v3
	v_cmp_eq_u32_e64 s[26:27], 11, v3
	v_cmp_eq_u32_e64 s[28:29], 12, v3
	v_cmp_eq_u32_e64 s[30:31], 13, v3
	v_cmp_eq_u32_e64 s[34:35], 14, v3
	v_cmp_eq_u32_e64 s[36:37], 15, v3
	s_setprio 0
	s_movk_i32 s41, 0x3fc
	s_mov_b32 s42, 0xffff0000
	s_mov_b32 s43, 0xfffd0000
	s_mov_b32 s45, 0xfffe0000
	s_mov_b64 s[46:47], 0x40000
	v_readlane_b32 s38, v253, 39
	v_readlane_b32 s39, v253, 40
	v_and_b32_e32 v136, 16, v1
	v_cmp_eq_u32_e32 vcc, 0, v136
	v_readlane_b32 s4, v254, 2
	s_lshl_b32 s4, s4, 1
	v_readlane_b32 s6, v253, 37
	v_readlane_b32 s5, v254, 3
	v_readlane_b32 s7, v253, 38
	s_add_u32 s4, s4, s6
	s_addc_u32 s5, 0, s7
	s_mul_i32 s5, s5, 12
	s_mul_hi_u32 s6, s4, 12
	s_add_i32 s6, s6, s5
	s_mul_i32 s4, s4, 12
	v_readlane_b32 s5, v253, 4
	s_add_u32 s4, s4, s5
	v_readlane_b32 s5, v253, 5
	s_addc_u32 s5, s6, s5
	s_lshl_b64 s[4:5], s[4:5], 14
	v_readlane_b32 s6, v253, 2
	v_ashrrev_i32_e32 v155, 31, v154
	s_add_u32 s4, s6, s4
	v_readlane_b32 s6, v253, 3
	s_addc_u32 s5, s6, s5
	s_waitcnt vmcnt(19)
	v_lshlrev_b64 v[4:5], 8, v[154:155]
	v_lshl_add_u64 v[4:5], s[4:5], 0, v[4:5]
	v_lshlrev_b32_e32 v6, 4, v3
	v_mov_b32_e32 v7, v2
	v_lshl_add_u64 v[4:5], v[4:5], 0, v[6:7]
	s_barrier
	global_store_dwordx4 v[4:5], v[68:71], off
	s_and_b64 vcc, exec, s[2:3]
	s_cbranch_vccnz .LBB0_1001
